# GEMM K-loops: per-segment s_setprio flips deleted, one static s_setprio 1 for waves 4-7 before each K-loop (reset after)
# speedup vs baseline: 1.0095x; 1.0095x over previous
; #define PG8_STAGE(bufoff, gbase, voff) do { _Pragma("unroll") for (int _i = 0; _i < 2; ++_i) \
;         __builtin_amdgcn_global_load_lds((const unsigned*)((const char*)(gbase) + (voff)[_i]), (PG8_LAS unsigned*)(lds + (bufoff) + ldsw + _i * 8192), 16, 0, 0); } while (0)
; #define PG8_LDA(dst, b, h) do { _Pragma("unroll") for (int m = 0; m < 4; ++m) _Pragma("unroll") for (int k = 0; k < 2; ++k) dst[m][k] = *(const PG8_LAS bf16x8*)(lds + PG8_SA(b, h) + aoff + m * 2048 + k * 1024); } while (0)
; #define PG8_LDB(dst, b, h) do { _Pragma("unroll") for (int n = 0; n < 2; ++n) _Pragma("unroll") for (int k = 0; k < 2; ++k) dst[n][k] = *(const PG8_LAS bf16x8*)(lds + PG8_SB(b, h) + boff + n * 2048 + k * 1024); } while (0)
; #define PG8_WAIT_V(n) asm volatile("s_waitcnt vmcnt(" #n ")" ::: "memory")
; #define PG8_WAIT_L(n) asm volatile("s_waitcnt lgkmcnt(" #n ")" ::: "memory")
; #define PG8_BAR __builtin_amdgcn_s_barrier()
; template <class Epi, class Sched, bool ALIGN_EPI = false, bool SP2 = false>
; __device__ __forceinline__ void gemm_phase(PG8_LAS unsigned char* lds, const Gemm g, const Sched& S, const Epi& E, const int tid_in) {
;     ...
;         const bool has_next = S.next(ui + 1, nxt);
;         const char* nA = has_next ? (const char*)g.A + (size_t)nxt.pm * tstep : cA; const char* nB = has_next ? (const char*)g.Bt + (size_t)nxt.pn * tstep : cB;
;         for (int t = 0; t < nt; t += 2) {
;             const bool last = (t == nt - 2);
;             const char* a1 = cA + (size_t)(t + 1) * kstep;
;             const char* a2 = last ? nA : cA + (size_t)(t + 2) * kstep; const char* b2 = last ? nB : cB + (size_t)(t + 2) * kstep;
;             const char* a3 = a2 + kstep; const char* b3 = b2 + kstep;
;             if (last && has_next) S.a_ready(nxt);
;             if constexpr (SP2) {
;             PG8_LDB(B0, 0, 0); PG8_LDB(B1, 0, 1); PG8_SCHED; PG8_LDA(At, 0, 0); PG8_STAGE(PG8_SA(1, 1), a1 + hstep, voffA);
;             PG8_WAIT_V(8); PG8_WAIT_L(0); PG8_BAR; PG8_MMA(0, 0, At, B0); PG8_MMA(0, 1, At, B1); PG8_BAR; PG8_SCHED;
;     ...
; #pragma unroll
;         for (int a = 0; a < 2; ++a)
; #pragma unroll
;             for (int b = 0; b < 2; ++b)
; #pragma unroll
;                 for (int m = 0; m < 4; ++m)
; #pragma unroll
;                     for (int n = 0; n < 2; ++n) acc[a][b][m][n] = (f32x4){0.f, 0.f, 0.f, 0.f};
;         cur = nxt; cA = nA; cB = nB; ++ui;
.LBB0_119:
	s_add_u32 s56, s8, 0x100
	v_mov_b32_e32 v0, 0
	s_addc_u32 s57, s9, 0
	s_mov_b32 s58, -2
	v_mov_b32_e32 v1, v0
	v_mov_b32_e32 v2, v0
	v_mov_b32_e32 v3, v0
	v_mov_b32_e32 v4, v0
	v_mov_b32_e32 v5, v0
	v_mov_b32_e32 v6, v0
	v_mov_b32_e32 v7, v0
	v_mov_b32_e32 v8, v0
	v_mov_b32_e32 v9, v0
	v_mov_b32_e32 v10, v0
	v_mov_b32_e32 v11, v0
	v_mov_b32_e32 v16, v0
	v_mov_b32_e32 v17, v0
	v_mov_b32_e32 v18, v0
	v_mov_b32_e32 v19, v0
	v_mov_b32_e32 v24, v0
	v_mov_b32_e32 v25, v0
	v_mov_b32_e32 v26, v0
	v_mov_b32_e32 v27, v0
	v_mov_b32_e32 v32, v0
	v_mov_b32_e32 v33, v0
	v_mov_b32_e32 v34, v0
	v_mov_b32_e32 v35, v0
	v_mov_b32_e32 v40, v0
	v_mov_b32_e32 v41, v0
	v_mov_b32_e32 v42, v0
	v_mov_b32_e32 v43, v0
	v_mov_b32_e32 v48, v0
	v_mov_b32_e32 v49, v0
	v_mov_b32_e32 v50, v0
	v_mov_b32_e32 v51, v0
	v_mov_b32_e32 v12, v0
	v_mov_b32_e32 v13, v0
	v_mov_b32_e32 v14, v0
	v_mov_b32_e32 v15, v0
	v_mov_b32_e32 v20, v0
	v_mov_b32_e32 v21, v0
	v_mov_b32_e32 v22, v0
	v_mov_b32_e32 v23, v0
	v_mov_b32_e32 v28, v0
	v_mov_b32_e32 v29, v0
	v_mov_b32_e32 v30, v0
	v_mov_b32_e32 v31, v0
	v_mov_b32_e32 v36, v0
	v_mov_b32_e32 v37, v0
	v_mov_b32_e32 v38, v0
	v_mov_b32_e32 v39, v0
	v_mov_b32_e32 v44, v0
	v_mov_b32_e32 v45, v0
	v_mov_b32_e32 v46, v0
	v_mov_b32_e32 v47, v0
	v_mov_b32_e32 v52, v0
	v_mov_b32_e32 v53, v0
	v_mov_b32_e32 v54, v0
	v_mov_b32_e32 v55, v0
	v_mov_b32_e32 v56, v0
	v_mov_b32_e32 v57, v0
	v_mov_b32_e32 v58, v0
	v_mov_b32_e32 v59, v0
	v_mov_b32_e32 v60, v0
	v_mov_b32_e32 v61, v0
	v_mov_b32_e32 v62, v0
	v_mov_b32_e32 v63, v0
	v_mov_b32_e32 v64, v0
	v_mov_b32_e32 v65, v0
	v_mov_b32_e32 v66, v0
	v_mov_b32_e32 v67, v0
	v_mov_b32_e32 v68, v0
	v_mov_b32_e32 v69, v0
	v_mov_b32_e32 v70, v0
	v_mov_b32_e32 v71, v0
	v_mov_b32_e32 v80, v0
	v_mov_b32_e32 v81, v0
	v_mov_b32_e32 v82, v0
	v_mov_b32_e32 v83, v0
	v_mov_b32_e32 v84, v0
	v_mov_b32_e32 v85, v0
	v_mov_b32_e32 v86, v0
	v_mov_b32_e32 v87, v0
	v_mov_b32_e32 v98, v0
	v_mov_b32_e32 v99, v0
	v_mov_b32_e32 v100, v0
	v_mov_b32_e32 v101, v0
	v_mov_b32_e32 v102, v0
	v_mov_b32_e32 v103, v0
	v_mov_b32_e32 v104, v0
	v_mov_b32_e32 v105, v0
	v_mov_b32_e32 v130, v0
	v_mov_b32_e32 v131, v0
	v_mov_b32_e32 v132, v0
	v_mov_b32_e32 v133, v0
	v_mov_b32_e32 v134, v0
	v_mov_b32_e32 v135, v0
	v_mov_b32_e32 v136, v0
	v_mov_b32_e32 v137, v0
	v_mov_b32_e32 v72, v0
	v_mov_b32_e32 v73, v0
	v_mov_b32_e32 v74, v0
	v_mov_b32_e32 v75, v0
	v_mov_b32_e32 v76, v0
	v_mov_b32_e32 v77, v0
	v_mov_b32_e32 v78, v0
	v_mov_b32_e32 v79, v0
	v_mov_b32_e32 v88, v0
	v_mov_b32_e32 v89, v0
	v_mov_b32_e32 v90, v0
	v_mov_b32_e32 v91, v0
	v_mov_b32_e32 v92, v0
	v_mov_b32_e32 v93, v0
	v_mov_b32_e32 v94, v0
	v_mov_b32_e32 v95, v0
	v_mov_b32_e32 v106, v0
	v_mov_b32_e32 v107, v0
	v_mov_b32_e32 v108, v0
	v_mov_b32_e32 v109, v0
	v_mov_b32_e32 v110, v0
	v_mov_b32_e32 v111, v0
	v_mov_b32_e32 v112, v0
	v_mov_b32_e32 v113, v0
	v_mov_b32_e32 v138, v0
	v_mov_b32_e32 v139, v0
	v_mov_b32_e32 v140, v0
	v_mov_b32_e32 v141, v0
	v_mov_b32_e32 v142, v0
	v_mov_b32_e32 v143, v0
	v_mov_b32_e32 v144, v0
	v_mov_b32_e32 v145, v0
	v_readfirstlane_b32 s70, v241
	s_nop 3
	s_lshr_b32 s70, s70, 6
	s_cmp_ge_u32 s70, 4
	s_cbranch_scc0 .Lprio_done_120
	s_setprio 1
.Lprio_done_120:
.LBB0_120:
	s_add_u32 s8, s44, 0x100
	s_addc_u32 s9, s45, 0
	s_add_i32 s59, 0, 0x10000
	s_cmpk_eq_i32 s58, 0x54
	s_cselect_b32 s13, s41, s9
	s_cselect_b32 s12, s40, s8
	s_cselect_b32 s11, s43, s57
	s_cselect_b32 s10, s42, s56
	s_add_i32 s60, 0, 0x14000
	v_add_u32_e32 v126, s59, v163
	v_add_u32_e32 v160, s60, v163
	ds_read_b128 v[114:117], v126
	ds_read_b128 v[118:121], v126 offset:1024
	ds_read_b128 v[122:125], v126 offset:2048
	ds_read_b128 v[126:129], v126 offset:3072
	ds_read_b128 v[156:159], v160
	ds_read_b128 v[166:169], v160 offset:1024
	ds_read_b128 v[170:173], v160 offset:2048
	ds_read_b128 v[174:177], v160 offset:3072
	v_lshl_add_u64 v[160:161], s[44:45], 0, v[152:153]
	s_add_i32 m0, s20, 0xc000
	ds_read_b128 v[178:181], v165
	ds_read_b128 v[184:187], v165 offset:1024
	ds_read_b128 v[196:199], v165 offset:2048
	ds_read_b128 v[200:203], v165 offset:3072
	ds_read_b128 v[204:207], v165 offset:4096
	ds_read_b128 v[208:211], v165 offset:5120
	ds_read_b128 v[212:215], v165 offset:6144
	ds_read_b128 v[216:219], v165 offset:7168
	global_load_lds_dwordx4 v[160:161], off
	v_lshl_add_u64 v[160:161], s[44:45], 0, v[154:155]
	s_add_i32 m0, s20, 0xe000
	s_nop 0
	global_load_lds_dwordx4 v[160:161], off
	s_waitcnt vmcnt(8)
	s_waitcnt lgkmcnt(0)
	s_barrier
	s_waitcnt lgkmcnt(0)
	v_mfma_f32_16x16x32_bf16 v[142:145], v[114:117], v[178:181], v[142:145]
	v_mfma_f32_16x16x32_bf16 v[138:141], v[122:125], v[178:181], v[138:141]
	v_mfma_f32_16x16x32_bf16 v[110:113], v[114:117], v[196:199], v[110:113]
	v_mfma_f32_16x16x32_bf16 v[106:109], v[122:125], v[196:199], v[106:109]
	v_mfma_f32_16x16x32_bf16 v[92:95], v[114:117], v[204:207], v[92:95]
	v_mfma_f32_16x16x32_bf16 v[88:91], v[122:125], v[204:207], v[88:91]
	v_mfma_f32_16x16x32_bf16 v[76:79], v[114:117], v[212:215], v[76:79]
	v_mfma_f32_16x16x32_bf16 v[72:75], v[122:125], v[212:215], v[72:75]
	v_mfma_f32_16x16x32_bf16 v[142:145], v[118:121], v[184:187], v[142:145]
	v_mfma_f32_16x16x32_bf16 v[138:141], v[126:129], v[184:187], v[138:141]
	v_mfma_f32_16x16x32_bf16 v[110:113], v[118:121], v[200:203], v[110:113]
	v_mfma_f32_16x16x32_bf16 v[106:109], v[126:129], v[200:203], v[106:109]
	v_mfma_f32_16x16x32_bf16 v[92:95], v[118:121], v[208:211], v[92:95]
	v_mfma_f32_16x16x32_bf16 v[88:91], v[126:129], v[208:211], v[88:91]
	v_mfma_f32_16x16x32_bf16 v[76:79], v[118:121], v[216:219], v[76:79]
	v_mfma_f32_16x16x32_bf16 v[72:75], v[126:129], v[216:219], v[72:75]
	v_mfma_f32_16x16x32_bf16 v[134:137], v[156:159], v[178:181], v[134:137]
	v_mfma_f32_16x16x32_bf16 v[130:133], v[170:173], v[178:181], v[130:133]
	v_mfma_f32_16x16x32_bf16 v[102:105], v[156:159], v[196:199], v[102:105]
	v_mfma_f32_16x16x32_bf16 v[98:101], v[170:173], v[196:199], v[98:101]
	v_mfma_f32_16x16x32_bf16 v[84:87], v[156:159], v[204:207], v[84:87]
	v_mfma_f32_16x16x32_bf16 v[80:83], v[170:173], v[204:207], v[80:83]
	v_mfma_f32_16x16x32_bf16 v[68:71], v[156:159], v[212:215], v[68:71]
	v_mfma_f32_16x16x32_bf16 v[64:67], v[170:173], v[212:215], v[64:67]
	v_mfma_f32_16x16x32_bf16 v[134:137], v[166:169], v[184:187], v[134:137]
	v_mfma_f32_16x16x32_bf16 v[130:133], v[174:177], v[184:187], v[130:133]
	v_mfma_f32_16x16x32_bf16 v[102:105], v[166:169], v[200:203], v[102:105]
	v_mfma_f32_16x16x32_bf16 v[98:101], v[174:177], v[200:203], v[98:101]
	v_mfma_f32_16x16x32_bf16 v[84:87], v[166:169], v[208:211], v[84:87]
	v_mfma_f32_16x16x32_bf16 v[80:83], v[174:177], v[208:211], v[80:83]
	v_mfma_f32_16x16x32_bf16 v[68:71], v[166:169], v[216:219], v[68:71]
	v_mfma_f32_16x16x32_bf16 v[64:67], v[174:177], v[216:219], v[64:67]
	s_barrier
; #define PG8_STAGE(bufoff, gbase, voff) do { _Pragma("unroll") for (int _i = 0; _i < 2; ++_i) \
;         __builtin_amdgcn_global_load_lds((const unsigned*)((const char*)(gbase) + (voff)[_i]), (PG8_LAS unsigned*)(lds + (bufoff) + ldsw + _i * 8192), 16, 0, 0); } while (0)
; #define PG8_LDA(dst, b, h) do { _Pragma("unroll") for (int m = 0; m < 4; ++m) _Pragma("unroll") for (int k = 0; k < 2; ++k) dst[m][k] = *(const PG8_LAS bf16x8*)(lds + PG8_SA(b, h) + aoff + m * 2048 + k * 1024); } while (0)
; #define PG8_LDB(dst, b, h) do { _Pragma("unroll") for (int n = 0; n < 2; ++n) _Pragma("unroll") for (int k = 0; k < 2; ++k) dst[n][k] = *(const PG8_LAS bf16x8*)(lds + PG8_SB(b, h) + boff + n * 2048 + k * 1024); } while (0)
; #define PG8_MMA(ai, bj, At, Bt) do { __builtin_amdgcn_s_setprio(1); _Pragma("unroll") for (int m = 0; m < 4; ++m) _Pragma("unroll") for (int n = 0; n < 2; ++n) _Pragma("unroll") for (int k = 0; k < 2; ++k) \
;         acc[ai][bj][m][n] = __builtin_amdgcn_mfma_f32_16x16x32_bf16(Bt[n][k], At[m][k], acc[ai][bj][m][n], 0, 0, 0); __builtin_amdgcn_s_setprio(0); } while (0)
; #define PG8_WAIT_V(n) asm volatile("s_waitcnt vmcnt(" #n ")" ::: "memory")
; #define PG8_WAIT_L(n) asm volatile("s_waitcnt lgkmcnt(" #n ")" ::: "memory")
; #define PG8_BAR __builtin_amdgcn_s_barrier()
; #define PG8_SCHED __builtin_amdgcn_sched_barrier(0)
; template <class Epi, class Sched, bool ALIGN_EPI = false, bool SP2 = false>
; __device__ __forceinline__ void gemm_phase(PG8_LAS unsigned char* lds, const Gemm g, const Sched& S, const Epi& E, const int tid_in) {
;     ...
;             PG8_LDA(At, 0, 1); PG8_STAGE(PG8_SB(0, 0), b2, voffB); PG8_STAGE(PG8_SB(0, 1), b2 + hstep, voffB); PG8_STAGE(PG8_SA(0, 0), a2, voffA);
;             PG8_WAIT_V(8); PG8_WAIT_L(0); PG8_BAR; PG8_MMA(1, 0, At, B0); PG8_MMA(1, 1, At, B1); PG8_BAR; PG8_SCHED;
;             PG8_LDB(B0, 1, 0); PG8_LDB(B1, 1, 1); PG8_SCHED; PG8_LDA(At, 1, 0); PG8_STAGE(PG8_SA(0, 1), a2 + hstep, voffA);
	s_add_i32 s44, s59, s19
	v_lshl_add_u64 v[160:161], s[10:11], 0, v[96:97]
	s_mov_b32 m0, s44
	ds_read_b128 v[178:181], v165 offset:16384
	ds_read_b128 v[184:187], v165 offset:17408
	ds_read_b128 v[196:199], v165 offset:18432
	ds_read_b128 v[200:203], v165 offset:19456
	ds_read_b128 v[204:207], v165 offset:20480
	ds_read_b128 v[208:211], v165 offset:21504
	ds_read_b128 v[212:215], v165 offset:22528
	ds_read_b128 v[216:219], v165 offset:23552
	global_load_lds_dwordx4 v[160:161], off
	s_add_i32 m0, s44, 0x2000
	s_add_u32 s44, s10, 0x160000
	v_lshl_add_u64 v[220:221], s[10:11], 0, v[150:151]
	s_addc_u32 s45, s11, 0
	s_add_i32 s59, s60, s19
	global_load_lds_dwordx4 v[220:221], off
	v_lshl_add_u64 v[222:223], s[44:45], 0, v[96:97]
	s_mov_b32 m0, s59
	v_lshl_add_u64 v[224:225], s[12:13], 0, v[148:149]
	global_load_lds_dwordx4 v[222:223], off
	v_lshl_add_u64 v[222:223], s[44:45], 0, v[150:151]
	s_add_i32 m0, s59, 0x2000
	s_nop 0
	global_load_lds_dwordx4 v[222:223], off
	v_lshl_add_u64 v[222:223], s[12:13], 0, v[146:147]
	s_mov_b32 m0, s20
	s_nop 0
	global_load_lds_dwordx4 v[222:223], off
	s_mov_b32 m0, s22
	s_nop 0
	global_load_lds_dwordx4 v[224:225], off
	s_waitcnt vmcnt(8)
	s_waitcnt lgkmcnt(0)
	s_barrier
	s_waitcnt lgkmcnt(0)
	v_mfma_f32_16x16x32_bf16 v[60:63], v[114:117], v[178:181], v[60:63]
	v_mfma_f32_16x16x32_bf16 v[56:59], v[122:125], v[178:181], v[56:59]
	v_mfma_f32_16x16x32_bf16 v[52:55], v[114:117], v[196:199], v[52:55]
	v_mfma_f32_16x16x32_bf16 v[44:47], v[122:125], v[196:199], v[44:47]
	v_mfma_f32_16x16x32_bf16 v[36:39], v[114:117], v[204:207], v[36:39]
	v_mfma_f32_16x16x32_bf16 v[28:31], v[122:125], v[204:207], v[28:31]
	v_mfma_f32_16x16x32_bf16 v[20:23], v[114:117], v[212:215], v[20:23]
	v_mfma_f32_16x16x32_bf16 v[12:15], v[122:125], v[212:215], v[12:15]
	v_mfma_f32_16x16x32_bf16 v[60:63], v[118:121], v[184:187], v[60:63]
	v_mfma_f32_16x16x32_bf16 v[56:59], v[126:129], v[184:187], v[56:59]
	v_mfma_f32_16x16x32_bf16 v[52:55], v[118:121], v[200:203], v[52:55]
	v_mfma_f32_16x16x32_bf16 v[44:47], v[126:129], v[200:203], v[44:47]
	v_mfma_f32_16x16x32_bf16 v[36:39], v[118:121], v[208:211], v[36:39]
	v_mfma_f32_16x16x32_bf16 v[28:31], v[126:129], v[208:211], v[28:31]
	v_mfma_f32_16x16x32_bf16 v[20:23], v[118:121], v[216:219], v[20:23]
	v_mfma_f32_16x16x32_bf16 v[12:15], v[126:129], v[216:219], v[12:15]
	v_mfma_f32_16x16x32_bf16 v[48:51], v[156:159], v[178:181], v[48:51]
	v_mfma_f32_16x16x32_bf16 v[40:43], v[170:173], v[178:181], v[40:43]
	v_mfma_f32_16x16x32_bf16 v[32:35], v[156:159], v[196:199], v[32:35]
	v_mfma_f32_16x16x32_bf16 v[24:27], v[170:173], v[196:199], v[24:27]
	v_mfma_f32_16x16x32_bf16 v[16:19], v[156:159], v[204:207], v[16:19]
	v_mfma_f32_16x16x32_bf16 v[8:11], v[170:173], v[204:207], v[8:11]
	v_mfma_f32_16x16x32_bf16 v[4:7], v[156:159], v[212:215], v[4:7]
	v_mfma_f32_16x16x32_bf16 v[0:3], v[170:173], v[212:215], v[0:3]
	v_mfma_f32_16x16x32_bf16 v[48:51], v[166:169], v[184:187], v[48:51]
	v_mfma_f32_16x16x32_bf16 v[40:43], v[174:177], v[184:187], v[40:43]
	v_mfma_f32_16x16x32_bf16 v[32:35], v[166:169], v[200:203], v[32:35]
	v_mfma_f32_16x16x32_bf16 v[24:27], v[174:177], v[200:203], v[24:27]
	v_mfma_f32_16x16x32_bf16 v[16:19], v[166:169], v[208:211], v[16:19]
	v_mfma_f32_16x16x32_bf16 v[8:11], v[174:177], v[208:211], v[8:11]
	v_mfma_f32_16x16x32_bf16 v[4:7], v[166:169], v[216:219], v[4:7]
	v_mfma_f32_16x16x32_bf16 v[0:3], v[174:177], v[216:219], v[0:3]
	s_barrier
	s_add_i32 s44, 0, 0x18000
	s_add_i32 s45, 0, 0x1c000
	v_add_u32_e32 v126, s44, v163
	v_add_u32_e32 v174, s45, v163
	ds_read_b128 v[114:117], v126
	ds_read_b128 v[118:121], v126 offset:1024
	ds_read_b128 v[122:125], v126 offset:2048
	ds_read_b128 v[126:129], v126 offset:3072
	ds_read_b128 v[156:159], v174
	ds_read_b128 v[166:169], v174 offset:1024
	ds_read_b128 v[170:173], v174 offset:2048
	ds_read_b128 v[174:177], v174 offset:3072
	s_add_u32 s12, s12, 0x160000
	s_addc_u32 s13, s13, 0
	s_mov_b32 m0, s23
	v_lshl_add_u64 v[242:243], s[12:13], 0, v[146:147]
	ds_read_b128 v[178:181], v165 offset:32768
	ds_read_b128 v[184:187], v165 offset:33792
	ds_read_b128 v[196:199], v165 offset:34816
	ds_read_b128 v[200:203], v165 offset:35840
	ds_read_b128 v[204:207], v165 offset:36864
	ds_read_b128 v[208:211], v165 offset:37888
	ds_read_b128 v[212:215], v165 offset:38912
	ds_read_b128 v[216:219], v165 offset:39936
	global_load_lds_dwordx4 v[242:243], off
	v_lshl_add_u64 v[242:243], s[12:13], 0, v[148:149]
	s_mov_b32 m0, s34
	s_nop 0
	global_load_lds_dwordx4 v[242:243], off
	s_waitcnt vmcnt(8)
	s_waitcnt lgkmcnt(0)
	s_barrier
; #define PG8_STAGE(bufoff, gbase, voff) do { _Pragma("unroll") for (int _i = 0; _i < 2; ++_i) \
;         __builtin_amdgcn_global_load_lds((const unsigned*)((const char*)(gbase) + (voff)[_i]), (PG8_LAS unsigned*)(lds + (bufoff) + ldsw + _i * 8192), 16, 0, 0); } while (0)
; #define PG8_LDA(dst, b, h) do { _Pragma("unroll") for (int m = 0; m < 4; ++m) _Pragma("unroll") for (int k = 0; k < 2; ++k) dst[m][k] = *(const PG8_LAS bf16x8*)(lds + PG8_SA(b, h) + aoff + m * 2048 + k * 1024); } while (0)
; #define PG8_WAIT_V(n) asm volatile("s_waitcnt vmcnt(" #n ")" ::: "memory")
; #define PG8_WAIT_L(n) asm volatile("s_waitcnt lgkmcnt(" #n ")" ::: "memory")
; #define PG8_BAR __builtin_amdgcn_s_barrier()
; template <class Epi, class Sched, bool ALIGN_EPI = false, bool SP2 = false>
; __device__ __forceinline__ void gemm_phase(PG8_LAS unsigned char* lds, const Gemm g, const Sched& S, const Epi& E, const int tid_in) {
;     ...
;         for (int t = 0; t < nt; t += 2) {
;             const bool last = (t == nt - 2);
;             const char* a1 = cA + (size_t)(t + 1) * kstep;
;             const char* a2 = last ? nA : cA + (size_t)(t + 2) * kstep; const char* b2 = last ? nB : cB + (size_t)(t + 2) * kstep;
;             const char* a3 = a2 + kstep; const char* b3 = b2 + kstep;
;             if (last && has_next) S.a_ready(nxt);
;             if constexpr (SP2) {
;             PG8_LDB(B0, 0, 0); PG8_LDB(B1, 0, 1); PG8_SCHED; PG8_LDA(At, 0, 0); PG8_STAGE(PG8_SA(1, 1), a1 + hstep, voffA);
;             PG8_WAIT_V(8); PG8_WAIT_L(0); PG8_BAR; PG8_MMA(0, 0, At, B0); PG8_MMA(0, 1, At, B1); PG8_BAR; PG8_SCHED;
;             PG8_LDA(At, 0, 1); PG8_STAGE(PG8_SB(0, 0), b2, voffB); PG8_STAGE(PG8_SB(0, 1), b2 + hstep, voffB); PG8_STAGE(PG8_SA(0, 0), a2, voffA);
;             PG8_WAIT_V(8); PG8_WAIT_L(0); PG8_BAR; PG8_MMA(1, 0, At, B0); PG8_MMA(1, 1, At, B1); PG8_BAR; PG8_SCHED;
;             PG8_LDB(B0, 1, 0); PG8_LDB(B1, 1, 1); PG8_SCHED; PG8_LDA(At, 1, 0); PG8_STAGE(PG8_SA(0, 1), a2 + hstep, voffA);
;             PG8_WAIT_V(8); PG8_WAIT_L(0); PG8_BAR; PG8_MMA(0, 0, At, B0); PG8_MMA(0, 1, At, B1); PG8_BAR; PG8_SCHED;
;             PG8_LDA(At, 1, 1); PG8_STAGE(PG8_SB(1, 0), b3, voffB); PG8_STAGE(PG8_SB(1, 1), b3 + hstep, voffB); PG8_STAGE(PG8_SA(1, 0), a3, voffA);
;             PG8_WAIT_V(8); PG8_WAIT_L(0); PG8_BAR; PG8_MMA(1, 0, At, B0); PG8_MMA(1, 1, At, B1); PG8_BAR; PG8_SCHED;
	s_waitcnt lgkmcnt(0)
	v_mfma_f32_16x16x32_bf16 v[142:145], v[114:117], v[178:181], v[142:145]
	v_mfma_f32_16x16x32_bf16 v[138:141], v[122:125], v[178:181], v[138:141]
	v_mfma_f32_16x16x32_bf16 v[110:113], v[114:117], v[196:199], v[110:113]
	v_mfma_f32_16x16x32_bf16 v[106:109], v[122:125], v[196:199], v[106:109]
	v_mfma_f32_16x16x32_bf16 v[92:95], v[114:117], v[204:207], v[92:95]
	v_mfma_f32_16x16x32_bf16 v[88:91], v[122:125], v[204:207], v[88:91]
	v_mfma_f32_16x16x32_bf16 v[76:79], v[114:117], v[212:215], v[76:79]
	v_mfma_f32_16x16x32_bf16 v[72:75], v[122:125], v[212:215], v[72:75]
	v_mfma_f32_16x16x32_bf16 v[142:145], v[118:121], v[184:187], v[142:145]
	v_mfma_f32_16x16x32_bf16 v[138:141], v[126:129], v[184:187], v[138:141]
	v_mfma_f32_16x16x32_bf16 v[110:113], v[118:121], v[200:203], v[110:113]
	v_mfma_f32_16x16x32_bf16 v[106:109], v[126:129], v[200:203], v[106:109]
	v_mfma_f32_16x16x32_bf16 v[92:95], v[118:121], v[208:211], v[92:95]
	v_mfma_f32_16x16x32_bf16 v[88:91], v[126:129], v[208:211], v[88:91]
	v_mfma_f32_16x16x32_bf16 v[76:79], v[118:121], v[216:219], v[76:79]
	v_mfma_f32_16x16x32_bf16 v[72:75], v[126:129], v[216:219], v[72:75]
	v_mfma_f32_16x16x32_bf16 v[134:137], v[156:159], v[178:181], v[134:137]
	v_mfma_f32_16x16x32_bf16 v[130:133], v[170:173], v[178:181], v[130:133]
	v_mfma_f32_16x16x32_bf16 v[102:105], v[156:159], v[196:199], v[102:105]
	v_mfma_f32_16x16x32_bf16 v[98:101], v[170:173], v[196:199], v[98:101]
	v_mfma_f32_16x16x32_bf16 v[84:87], v[156:159], v[204:207], v[84:87]
	v_mfma_f32_16x16x32_bf16 v[80:83], v[170:173], v[204:207], v[80:83]
	v_mfma_f32_16x16x32_bf16 v[68:71], v[156:159], v[212:215], v[68:71]
	v_mfma_f32_16x16x32_bf16 v[64:67], v[170:173], v[212:215], v[64:67]
	v_mfma_f32_16x16x32_bf16 v[134:137], v[166:169], v[184:187], v[134:137]
	v_mfma_f32_16x16x32_bf16 v[130:133], v[174:177], v[184:187], v[130:133]
	v_mfma_f32_16x16x32_bf16 v[102:105], v[166:169], v[200:203], v[102:105]
	v_mfma_f32_16x16x32_bf16 v[98:101], v[174:177], v[200:203], v[98:101]
	v_mfma_f32_16x16x32_bf16 v[84:87], v[166:169], v[208:211], v[84:87]
	v_mfma_f32_16x16x32_bf16 v[80:83], v[174:177], v[208:211], v[80:83]
	v_mfma_f32_16x16x32_bf16 v[68:71], v[166:169], v[216:219], v[68:71]
	v_mfma_f32_16x16x32_bf16 v[64:67], v[174:177], v[216:219], v[64:67]
	s_barrier
	s_add_i32 s12, s44, s19
	v_lshl_add_u64 v[160:161], v[160:161], 0, s[2:3]
	s_mov_b32 m0, s12
	ds_read_b128 v[178:181], v165 offset:49152
	ds_read_b128 v[184:187], v165 offset:50176
	ds_read_b128 v[196:199], v165 offset:51200
	ds_read_b128 v[200:203], v165 offset:52224
	ds_read_b128 v[204:207], v165 offset:53248
	ds_read_b128 v[208:211], v165 offset:54272
	ds_read_b128 v[212:215], v165 offset:55296
	ds_read_b128 v[216:219], v165 offset:56320
	global_load_lds_dwordx4 v[160:161], off
	s_add_i32 m0, s12, 0x2000
	s_add_u32 s10, s10, 0x160080
	v_lshl_add_u64 v[160:161], v[220:221], 0, s[2:3]
	s_addc_u32 s11, s11, 0
	s_add_i32 s12, s45, s19
	global_load_lds_dwordx4 v[160:161], off
	v_lshl_add_u64 v[160:161], s[10:11], 0, v[96:97]
	s_mov_b32 m0, s12
	s_nop 0
	global_load_lds_dwordx4 v[160:161], off
	v_lshl_add_u64 v[160:161], s[10:11], 0, v[150:151]
	s_add_i32 m0, s12, 0x2000
	s_nop 0
	global_load_lds_dwordx4 v[160:161], off
	v_lshl_add_u64 v[160:161], v[222:223], 0, s[2:3]
	s_mov_b32 m0, s49
	s_nop 0
	global_load_lds_dwordx4 v[160:161], off
	v_lshl_add_u64 v[160:161], v[224:225], 0, s[2:3]
	s_mov_b32 m0, s50
	s_nop 0
	global_load_lds_dwordx4 v[160:161], off
	s_waitcnt vmcnt(8)
	s_waitcnt lgkmcnt(0)
	s_barrier
	s_waitcnt lgkmcnt(0)
	v_mfma_f32_16x16x32_bf16 v[60:63], v[114:117], v[178:181], v[60:63]
	v_mfma_f32_16x16x32_bf16 v[56:59], v[122:125], v[178:181], v[56:59]
	v_mfma_f32_16x16x32_bf16 v[52:55], v[114:117], v[196:199], v[52:55]
	v_mfma_f32_16x16x32_bf16 v[44:47], v[122:125], v[196:199], v[44:47]
	v_mfma_f32_16x16x32_bf16 v[36:39], v[114:117], v[204:207], v[36:39]
	v_mfma_f32_16x16x32_bf16 v[28:31], v[122:125], v[204:207], v[28:31]
	v_mfma_f32_16x16x32_bf16 v[20:23], v[114:117], v[212:215], v[20:23]
	v_mfma_f32_16x16x32_bf16 v[12:15], v[122:125], v[212:215], v[12:15]
	v_mfma_f32_16x16x32_bf16 v[60:63], v[118:121], v[184:187], v[60:63]
	v_mfma_f32_16x16x32_bf16 v[56:59], v[126:129], v[184:187], v[56:59]
	v_mfma_f32_16x16x32_bf16 v[52:55], v[118:121], v[200:203], v[52:55]
	v_mfma_f32_16x16x32_bf16 v[44:47], v[126:129], v[200:203], v[44:47]
	v_mfma_f32_16x16x32_bf16 v[36:39], v[118:121], v[208:211], v[36:39]
	v_mfma_f32_16x16x32_bf16 v[28:31], v[126:129], v[208:211], v[28:31]
	v_mfma_f32_16x16x32_bf16 v[20:23], v[118:121], v[216:219], v[20:23]
	v_mfma_f32_16x16x32_bf16 v[12:15], v[126:129], v[216:219], v[12:15]
	v_mfma_f32_16x16x32_bf16 v[48:51], v[156:159], v[178:181], v[48:51]
	v_mfma_f32_16x16x32_bf16 v[40:43], v[170:173], v[178:181], v[40:43]
	v_mfma_f32_16x16x32_bf16 v[32:35], v[156:159], v[196:199], v[32:35]
	v_mfma_f32_16x16x32_bf16 v[24:27], v[170:173], v[196:199], v[24:27]
	v_mfma_f32_16x16x32_bf16 v[16:19], v[156:159], v[204:207], v[16:19]
	v_mfma_f32_16x16x32_bf16 v[8:11], v[170:173], v[204:207], v[8:11]
	v_mfma_f32_16x16x32_bf16 v[4:7], v[156:159], v[212:215], v[4:7]
	v_mfma_f32_16x16x32_bf16 v[0:3], v[170:173], v[212:215], v[0:3]
	v_mfma_f32_16x16x32_bf16 v[48:51], v[166:169], v[184:187], v[48:51]
	v_mfma_f32_16x16x32_bf16 v[40:43], v[174:177], v[184:187], v[40:43]
	v_mfma_f32_16x16x32_bf16 v[32:35], v[166:169], v[200:203], v[32:35]
	v_mfma_f32_16x16x32_bf16 v[24:27], v[174:177], v[200:203], v[24:27]
	v_mfma_f32_16x16x32_bf16 v[16:19], v[166:169], v[208:211], v[16:19]
	v_mfma_f32_16x16x32_bf16 v[8:11], v[174:177], v[208:211], v[8:11]
	v_mfma_f32_16x16x32_bf16 v[4:7], v[166:169], v[216:219], v[4:7]
	v_mfma_f32_16x16x32_bf16 v[0:3], v[174:177], v[216:219], v[0:3]
	s_barrier
	s_add_i32 s58, s58, 2
	s_add_u32 s56, s56, 0x100
	s_addc_u32 s57, s57, 0
	s_cmpk_gt_u32 s58, 0x55
	s_mov_b64 s[44:45], s[8:9]
	s_cbranch_scc0 .LBB0_120
	s_setprio 0
	s_and_b64 vcc, exec, s[36:37]
	s_cbranch_vccz .LBB0_123
	s_barrier

; #define PG8_STAGE(bufoff, gbase, voff) do { _Pragma("unroll") for (int _i = 0; _i < 2; ++_i) \
;         __builtin_amdgcn_global_load_lds((const unsigned*)((const char*)(gbase) + (voff)[_i]), (PG8_LAS unsigned*)(lds + (bufoff) + ldsw + _i * 8192), 16, 0, 0); } while (0)
; #define PG8_LDA(dst, b, h) do { _Pragma("unroll") for (int m = 0; m < 4; ++m) _Pragma("unroll") for (int k = 0; k < 2; ++k) dst[m][k] = *(const PG8_LAS bf16x8*)(lds + PG8_SA(b, h) + aoff + m * 2048 + k * 1024); } while (0)
; #define PG8_LDB(dst, b, h) do { _Pragma("unroll") for (int n = 0; n < 2; ++n) _Pragma("unroll") for (int k = 0; k < 2; ++k) dst[n][k] = *(const PG8_LAS bf16x8*)(lds + PG8_SB(b, h) + boff + n * 2048 + k * 1024); } while (0)
; #define PG8_WAIT_V(n) asm volatile("s_waitcnt vmcnt(" #n ")" ::: "memory")
; #define PG8_WAIT_L(n) asm volatile("s_waitcnt lgkmcnt(" #n ")" ::: "memory")
; #define PG8_BAR __builtin_amdgcn_s_barrier()
; template <class Epi, class Sched, bool ALIGN_EPI = false, bool SP2 = false>
; __device__ __forceinline__ void gemm_phase(PG8_LAS unsigned char* lds, const Gemm g, const Sched& S, const Epi& E, const int tid_in) {
;     ...
;         const bool has_next = S.next(ui + 1, nxt);
;         const char* nA = has_next ? (const char*)g.A + (size_t)nxt.pm * tstep : cA; const char* nB = has_next ? (const char*)g.Bt + (size_t)nxt.pn * tstep : cB;
;         for (int t = 0; t < nt; t += 2) {
;             const bool last = (t == nt - 2);
;             const char* a1 = cA + (size_t)(t + 1) * kstep;
;             const char* a2 = last ? nA : cA + (size_t)(t + 2) * kstep; const char* b2 = last ? nB : cB + (size_t)(t + 2) * kstep;
;             const char* a3 = a2 + kstep; const char* b3 = b2 + kstep;
;             if (last && has_next) S.a_ready(nxt);
;             if constexpr (SP2) {
;             PG8_LDB(B0, 0, 0); PG8_LDB(B1, 0, 1); PG8_SCHED; PG8_LDA(At, 0, 0); PG8_STAGE(PG8_SA(1, 1), a1 + hstep, voffA);
;             PG8_WAIT_V(8); PG8_WAIT_L(0); PG8_BAR; PG8_MMA(0, 0, At, B0); PG8_MMA(0, 1, At, B1); PG8_BAR; PG8_SCHED;
;     ...
; #pragma unroll
;         for (int a = 0; a < 2; ++a)
; #pragma unroll
;             for (int b = 0; b < 2; ++b)
; #pragma unroll
;                 for (int m = 0; m < 4; ++m)
; #pragma unroll
;                     for (int n = 0; n < 2; ++n) acc[a][b][m][n] = (f32x4){0.f, 0.f, 0.f, 0.f};
;         cur = nxt; cA = nA; cB = nB; ++ui;
.LBB0_137:
	s_ashr_i32 s43, s42, 31
	s_lshl_b64 s[12:13], s[42:43], 20
	v_readlane_b32 s44, v255, 4
	v_readlane_b32 s45, v255, 5
	s_add_u32 s44, s44, s12
	s_addc_u32 s45, s45, s13
	s_and_b64 s[12:13], s[38:39], exec
	s_cselect_b32 s12, s45, s11
	s_cselect_b32 s13, s44, s10
	s_ashr_i32 s41, s40, 31
	s_lshl_b64 s[48:49], s[40:41], 20
	s_add_u32 s48, s14, s48
	s_addc_u32 s49, s15, s49
	s_and_b64 s[50:51], s[38:39], exec
	s_cselect_b32 s41, s49, s9
	s_cselect_b32 s43, s48, s8
	s_add_u32 s50, s10, 0x80080
	s_addc_u32 s51, s11, 0
	s_add_u32 s56, s8, 0x100
	v_mov_b32_e32 v0, 0
	s_addc_u32 s57, s9, 0
	s_mov_b32 s58, -2
	v_mov_b32_e32 v1, v0
	v_mov_b32_e32 v2, v0
	v_mov_b32_e32 v3, v0
	v_mov_b32_e32 v8, v0
	v_mov_b32_e32 v9, v0
	v_mov_b32_e32 v10, v0
	v_mov_b32_e32 v11, v0
	v_mov_b32_e32 v16, v0
	v_mov_b32_e32 v17, v0
	v_mov_b32_e32 v18, v0
	v_mov_b32_e32 v19, v0
	v_mov_b32_e32 v24, v0
	v_mov_b32_e32 v25, v0
	v_mov_b32_e32 v26, v0
	v_mov_b32_e32 v27, v0
	v_mov_b32_e32 v32, v0
	v_mov_b32_e32 v33, v0
	v_mov_b32_e32 v34, v0
	v_mov_b32_e32 v35, v0
	v_mov_b32_e32 v40, v0
	v_mov_b32_e32 v41, v0
	v_mov_b32_e32 v42, v0
	v_mov_b32_e32 v43, v0
	v_mov_b32_e32 v48, v0
	v_mov_b32_e32 v49, v0
	v_mov_b32_e32 v50, v0
	v_mov_b32_e32 v51, v0
	v_mov_b32_e32 v56, v0
	v_mov_b32_e32 v57, v0
	v_mov_b32_e32 v58, v0
	v_mov_b32_e32 v59, v0
	v_mov_b32_e32 v4, v0
	v_mov_b32_e32 v5, v0
	v_mov_b32_e32 v6, v0
	v_mov_b32_e32 v7, v0
	v_mov_b32_e32 v12, v0
	v_mov_b32_e32 v13, v0
	v_mov_b32_e32 v14, v0
	v_mov_b32_e32 v15, v0
	v_mov_b32_e32 v20, v0
	v_mov_b32_e32 v21, v0
	v_mov_b32_e32 v22, v0
	v_mov_b32_e32 v23, v0
	v_mov_b32_e32 v28, v0
	v_mov_b32_e32 v29, v0
	v_mov_b32_e32 v30, v0
	v_mov_b32_e32 v31, v0
	v_mov_b32_e32 v36, v0
	v_mov_b32_e32 v37, v0
	v_mov_b32_e32 v38, v0
	v_mov_b32_e32 v39, v0
	v_mov_b32_e32 v44, v0
	v_mov_b32_e32 v45, v0
	v_mov_b32_e32 v46, v0
	v_mov_b32_e32 v47, v0
	v_mov_b32_e32 v52, v0
	v_mov_b32_e32 v53, v0
	v_mov_b32_e32 v54, v0
	v_mov_b32_e32 v55, v0
	v_mov_b32_e32 v60, v0
	v_mov_b32_e32 v61, v0
	v_mov_b32_e32 v62, v0
	v_mov_b32_e32 v63, v0
	v_mov_b32_e32 v64, v0
	v_mov_b32_e32 v65, v0
	v_mov_b32_e32 v66, v0
	v_mov_b32_e32 v67, v0
	v_mov_b32_e32 v72, v0
	v_mov_b32_e32 v73, v0
	v_mov_b32_e32 v74, v0
	v_mov_b32_e32 v75, v0
	v_mov_b32_e32 v80, v0
	v_mov_b32_e32 v81, v0
	v_mov_b32_e32 v82, v0
	v_mov_b32_e32 v83, v0
	v_mov_b32_e32 v88, v0
	v_mov_b32_e32 v89, v0
	v_mov_b32_e32 v90, v0
	v_mov_b32_e32 v91, v0
	v_mov_b32_e32 v98, v0
	v_mov_b32_e32 v99, v0
	v_mov_b32_e32 v100, v0
	v_mov_b32_e32 v101, v0
	v_mov_b32_e32 v106, v0
	v_mov_b32_e32 v107, v0
	v_mov_b32_e32 v108, v0
	v_mov_b32_e32 v109, v0
	v_mov_b32_e32 v114, v0
	v_mov_b32_e32 v115, v0
	v_mov_b32_e32 v116, v0
	v_mov_b32_e32 v117, v0
	v_mov_b32_e32 v122, v0
	v_mov_b32_e32 v123, v0
	v_mov_b32_e32 v124, v0
	v_mov_b32_e32 v125, v0
	v_mov_b32_e32 v68, v0
	v_mov_b32_e32 v69, v0
	v_mov_b32_e32 v70, v0
	v_mov_b32_e32 v71, v0
	v_mov_b32_e32 v76, v0
	v_mov_b32_e32 v77, v0
	v_mov_b32_e32 v78, v0
	v_mov_b32_e32 v79, v0
	v_mov_b32_e32 v84, v0
	v_mov_b32_e32 v85, v0
	v_mov_b32_e32 v86, v0
	v_mov_b32_e32 v87, v0
	v_mov_b32_e32 v92, v0
	v_mov_b32_e32 v93, v0
	v_mov_b32_e32 v94, v0
	v_mov_b32_e32 v95, v0
	v_mov_b32_e32 v102, v0
	v_mov_b32_e32 v103, v0
	v_mov_b32_e32 v104, v0
	v_mov_b32_e32 v105, v0
	v_mov_b32_e32 v110, v0
	v_mov_b32_e32 v111, v0
	v_mov_b32_e32 v112, v0
	v_mov_b32_e32 v113, v0
	v_mov_b32_e32 v118, v0
	v_mov_b32_e32 v119, v0
	v_mov_b32_e32 v120, v0
	v_mov_b32_e32 v121, v0
	v_mov_b32_e32 v126, v0
	v_mov_b32_e32 v127, v0
	v_mov_b32_e32 v128, v0
	v_mov_b32_e32 v129, v0
	v_readfirstlane_b32 s70, v241
	s_nop 3
	s_lshr_b32 s70, s70, 6
	s_cmp_ge_u32 s70, 4
	s_cbranch_scc0 .Lprio_done_138
	s_setprio 1
.Lprio_done_138:
.LBB0_138:
	s_add_u32 s8, s50, 0xfff80080
	s_addc_u32 s9, s51, -1
	s_add_i32 s59, 0, 0x10000
	s_cmp_eq_u32 s58, 28
	s_cselect_b32 s11, s12, s9
	s_cselect_b32 s10, s13, s8
	s_cselect_b32 s9, s41, s57
	s_cselect_b32 s8, s43, s56
	s_add_i32 s62, 0, 0x14000
	v_add_u32_e32 v156, s59, v141
	v_add_u32_e32 v172, s62, v141
	ds_read_b128 v[144:147], v156
	ds_read_b128 v[148:151], v156 offset:1024
	ds_read_b128 v[152:155], v156 offset:2048
	ds_read_b128 v[156:159], v156 offset:3072
	ds_read_b128 v[160:163], v172
	ds_read_b128 v[164:167], v172 offset:1024
	ds_read_b128 v[168:171], v172 offset:2048
	ds_read_b128 v[172:175], v172 offset:3072
	v_lshl_add_u64 v[180:181], s[50:51], 0, v[136:137]
	s_add_i32 m0, s20, 0xc000
	ds_read_b128 v[176:179], v143
	ds_read_b128 v[184:187], v143 offset:1024
	ds_read_b128 v[196:199], v143 offset:2048
	ds_read_b128 v[200:203], v143 offset:3072
	ds_read_b128 v[204:207], v143 offset:4096
	ds_read_b128 v[208:211], v143 offset:5120
	ds_read_b128 v[212:215], v143 offset:6144
	ds_read_b128 v[216:219], v143 offset:7168
	global_load_lds_dwordx4 v[180:181], off
	v_lshl_add_u64 v[180:181], s[50:51], 0, v[138:139]
	s_add_i32 m0, s20, 0xe000
	s_nop 0
	global_load_lds_dwordx4 v[180:181], off
	s_waitcnt vmcnt(8)
	s_waitcnt lgkmcnt(0)
	s_barrier
; #define PG8_STAGE(bufoff, gbase, voff) do { _Pragma("unroll") for (int _i = 0; _i < 2; ++_i) \
;         __builtin_amdgcn_global_load_lds((const unsigned*)((const char*)(gbase) + (voff)[_i]), (PG8_LAS unsigned*)(lds + (bufoff) + ldsw + _i * 8192), 16, 0, 0); } while (0)
; #define PG8_LDA(dst, b, h) do { _Pragma("unroll") for (int m = 0; m < 4; ++m) _Pragma("unroll") for (int k = 0; k < 2; ++k) dst[m][k] = *(const PG8_LAS bf16x8*)(lds + PG8_SA(b, h) + aoff + m * 2048 + k * 1024); } while (0)
; #define PG8_LDB(dst, b, h) do { _Pragma("unroll") for (int n = 0; n < 2; ++n) _Pragma("unroll") for (int k = 0; k < 2; ++k) dst[n][k] = *(const PG8_LAS bf16x8*)(lds + PG8_SB(b, h) + boff + n * 2048 + k * 1024); } while (0)
; #define PG8_MMA(ai, bj, At, Bt) do { __builtin_amdgcn_s_setprio(1); _Pragma("unroll") for (int m = 0; m < 4; ++m) _Pragma("unroll") for (int n = 0; n < 2; ++n) _Pragma("unroll") for (int k = 0; k < 2; ++k) \
;         acc[ai][bj][m][n] = __builtin_amdgcn_mfma_f32_16x16x32_bf16(Bt[n][k], At[m][k], acc[ai][bj][m][n], 0, 0, 0); __builtin_amdgcn_s_setprio(0); } while (0)
; #define PG8_WAIT_V(n) asm volatile("s_waitcnt vmcnt(" #n ")" ::: "memory")
; #define PG8_WAIT_L(n) asm volatile("s_waitcnt lgkmcnt(" #n ")" ::: "memory")
; #define PG8_BAR __builtin_amdgcn_s_barrier()
; #define PG8_SCHED __builtin_amdgcn_sched_barrier(0)
; template <class Epi, class Sched, bool ALIGN_EPI = false, bool SP2 = false>
; __device__ __forceinline__ void gemm_phase(PG8_LAS unsigned char* lds, const Gemm g, const Sched& S, const Epi& E, const int tid_in) {
;     ...
;             PG8_LDB(B0, 0, 0); PG8_LDB(B1, 0, 1); PG8_SCHED; PG8_LDA(At, 0, 0); PG8_STAGE(PG8_SA(1, 1), a1 + hstep, voffA);
;             PG8_WAIT_V(8); PG8_WAIT_L(0); PG8_BAR; PG8_MMA(0, 0, At, B0); PG8_MMA(0, 1, At, B1); PG8_BAR; PG8_SCHED;
;             PG8_LDA(At, 0, 1); PG8_STAGE(PG8_SB(0, 0), b2, voffB); PG8_STAGE(PG8_SB(0, 1), b2 + hstep, voffB); PG8_STAGE(PG8_SA(0, 0), a2, voffA);
;             PG8_WAIT_V(8); PG8_WAIT_L(0); PG8_BAR; PG8_MMA(1, 0, At, B0); PG8_MMA(1, 1, At, B1); PG8_BAR; PG8_SCHED;
	s_waitcnt lgkmcnt(0)
	v_mfma_f32_16x16x32_bf16 v[126:129], v[144:147], v[176:179], v[126:129]
	v_mfma_f32_16x16x32_bf16 v[118:121], v[152:155], v[176:179], v[118:121]
	v_mfma_f32_16x16x32_bf16 v[110:113], v[144:147], v[196:199], v[110:113]
	v_mfma_f32_16x16x32_bf16 v[102:105], v[152:155], v[196:199], v[102:105]
	v_mfma_f32_16x16x32_bf16 v[92:95], v[144:147], v[204:207], v[92:95]
	v_mfma_f32_16x16x32_bf16 v[84:87], v[152:155], v[204:207], v[84:87]
	v_mfma_f32_16x16x32_bf16 v[76:79], v[144:147], v[212:215], v[76:79]
	v_mfma_f32_16x16x32_bf16 v[68:71], v[152:155], v[212:215], v[68:71]
	v_mfma_f32_16x16x32_bf16 v[126:129], v[148:151], v[184:187], v[126:129]
	v_mfma_f32_16x16x32_bf16 v[118:121], v[156:159], v[184:187], v[118:121]
	v_mfma_f32_16x16x32_bf16 v[110:113], v[148:151], v[200:203], v[110:113]
	v_mfma_f32_16x16x32_bf16 v[102:105], v[156:159], v[200:203], v[102:105]
	v_mfma_f32_16x16x32_bf16 v[92:95], v[148:151], v[208:211], v[92:95]
	v_mfma_f32_16x16x32_bf16 v[84:87], v[156:159], v[208:211], v[84:87]
	v_mfma_f32_16x16x32_bf16 v[76:79], v[148:151], v[216:219], v[76:79]
	v_mfma_f32_16x16x32_bf16 v[68:71], v[156:159], v[216:219], v[68:71]
	v_mfma_f32_16x16x32_bf16 v[122:125], v[160:163], v[176:179], v[122:125]
	v_mfma_f32_16x16x32_bf16 v[114:117], v[168:171], v[176:179], v[114:117]
	v_mfma_f32_16x16x32_bf16 v[106:109], v[160:163], v[196:199], v[106:109]
	v_mfma_f32_16x16x32_bf16 v[98:101], v[168:171], v[196:199], v[98:101]
	v_mfma_f32_16x16x32_bf16 v[88:91], v[160:163], v[204:207], v[88:91]
	v_mfma_f32_16x16x32_bf16 v[80:83], v[168:171], v[204:207], v[80:83]
	v_mfma_f32_16x16x32_bf16 v[72:75], v[160:163], v[212:215], v[72:75]
	v_mfma_f32_16x16x32_bf16 v[64:67], v[168:171], v[212:215], v[64:67]
	v_mfma_f32_16x16x32_bf16 v[122:125], v[164:167], v[184:187], v[122:125]
	v_mfma_f32_16x16x32_bf16 v[114:117], v[172:175], v[184:187], v[114:117]
	v_mfma_f32_16x16x32_bf16 v[106:109], v[164:167], v[200:203], v[106:109]
	v_mfma_f32_16x16x32_bf16 v[98:101], v[172:175], v[200:203], v[98:101]
	v_mfma_f32_16x16x32_bf16 v[88:91], v[164:167], v[208:211], v[88:91]
	v_mfma_f32_16x16x32_bf16 v[80:83], v[172:175], v[208:211], v[80:83]
	v_mfma_f32_16x16x32_bf16 v[72:75], v[164:167], v[216:219], v[72:75]
	v_mfma_f32_16x16x32_bf16 v[64:67], v[172:175], v[216:219], v[64:67]
	s_barrier
	s_add_i32 s59, s59, s19
	v_lshl_add_u64 v[180:181], s[8:9], 0, v[96:97]
	s_mov_b32 m0, s59
	ds_read_b128 v[176:179], v143 offset:16384
	ds_read_b128 v[184:187], v143 offset:17408
	ds_read_b128 v[196:199], v143 offset:18432
	ds_read_b128 v[200:203], v143 offset:19456
	ds_read_b128 v[204:207], v143 offset:20480
	ds_read_b128 v[208:211], v143 offset:21504
	ds_read_b128 v[212:215], v143 offset:22528
	ds_read_b128 v[216:219], v143 offset:23552
	global_load_lds_dwordx4 v[180:181], off
	s_add_i32 m0, s59, 0x2000
	s_add_u32 s60, s8, 0x80000
	v_lshl_add_u64 v[220:221], s[8:9], 0, v[130:131]
	s_addc_u32 s61, s9, 0
	s_add_i32 s59, s62, s19
	global_load_lds_dwordx4 v[220:221], off
	v_lshl_add_u64 v[222:223], s[60:61], 0, v[96:97]
	s_mov_b32 m0, s59
	v_lshl_add_u64 v[224:225], s[10:11], 0, v[132:133]
	global_load_lds_dwordx4 v[222:223], off
	v_lshl_add_u64 v[222:223], s[60:61], 0, v[130:131]
	s_add_i32 m0, s59, 0x2000
	s_nop 0
	global_load_lds_dwordx4 v[222:223], off
	v_lshl_add_u64 v[222:223], s[10:11], 0, v[134:135]
	s_mov_b32 m0, s20
	s_nop 0
	global_load_lds_dwordx4 v[222:223], off
	s_mov_b32 m0, s22
	s_nop 0
	global_load_lds_dwordx4 v[224:225], off
	s_waitcnt vmcnt(8)
	s_waitcnt lgkmcnt(0)
	s_barrier
	s_waitcnt lgkmcnt(0)
	v_mfma_f32_16x16x32_bf16 v[60:63], v[144:147], v[176:179], v[60:63]
	v_mfma_f32_16x16x32_bf16 v[52:55], v[152:155], v[176:179], v[52:55]
	v_mfma_f32_16x16x32_bf16 v[44:47], v[144:147], v[196:199], v[44:47]
	v_mfma_f32_16x16x32_bf16 v[36:39], v[152:155], v[196:199], v[36:39]
	v_mfma_f32_16x16x32_bf16 v[28:31], v[144:147], v[204:207], v[28:31]
	v_mfma_f32_16x16x32_bf16 v[20:23], v[152:155], v[204:207], v[20:23]
	v_mfma_f32_16x16x32_bf16 v[12:15], v[144:147], v[212:215], v[12:15]
	v_mfma_f32_16x16x32_bf16 v[4:7], v[152:155], v[212:215], v[4:7]
	v_mfma_f32_16x16x32_bf16 v[60:63], v[148:151], v[184:187], v[60:63]
	v_mfma_f32_16x16x32_bf16 v[52:55], v[156:159], v[184:187], v[52:55]
	v_mfma_f32_16x16x32_bf16 v[44:47], v[148:151], v[200:203], v[44:47]
	v_mfma_f32_16x16x32_bf16 v[36:39], v[156:159], v[200:203], v[36:39]
	v_mfma_f32_16x16x32_bf16 v[28:31], v[148:151], v[208:211], v[28:31]
	v_mfma_f32_16x16x32_bf16 v[20:23], v[156:159], v[208:211], v[20:23]
	v_mfma_f32_16x16x32_bf16 v[12:15], v[148:151], v[216:219], v[12:15]
	v_mfma_f32_16x16x32_bf16 v[4:7], v[156:159], v[216:219], v[4:7]
	v_mfma_f32_16x16x32_bf16 v[56:59], v[160:163], v[176:179], v[56:59]
	v_mfma_f32_16x16x32_bf16 v[48:51], v[168:171], v[176:179], v[48:51]
	v_mfma_f32_16x16x32_bf16 v[40:43], v[160:163], v[196:199], v[40:43]
	v_mfma_f32_16x16x32_bf16 v[32:35], v[168:171], v[196:199], v[32:35]
	v_mfma_f32_16x16x32_bf16 v[24:27], v[160:163], v[204:207], v[24:27]
	v_mfma_f32_16x16x32_bf16 v[16:19], v[168:171], v[204:207], v[16:19]
	v_mfma_f32_16x16x32_bf16 v[8:11], v[160:163], v[212:215], v[8:11]
	v_mfma_f32_16x16x32_bf16 v[0:3], v[168:171], v[212:215], v[0:3]
	v_mfma_f32_16x16x32_bf16 v[56:59], v[164:167], v[184:187], v[56:59]
	v_mfma_f32_16x16x32_bf16 v[48:51], v[172:175], v[184:187], v[48:51]
	v_mfma_f32_16x16x32_bf16 v[40:43], v[164:167], v[200:203], v[40:43]
	v_mfma_f32_16x16x32_bf16 v[32:35], v[172:175], v[200:203], v[32:35]
	v_mfma_f32_16x16x32_bf16 v[24:27], v[164:167], v[208:211], v[24:27]
	v_mfma_f32_16x16x32_bf16 v[16:19], v[172:175], v[208:211], v[16:19]
	v_mfma_f32_16x16x32_bf16 v[8:11], v[164:167], v[216:219], v[8:11]
	v_mfma_f32_16x16x32_bf16 v[0:3], v[172:175], v[216:219], v[0:3]
	s_barrier
; #define PG8_STAGE(bufoff, gbase, voff) do { _Pragma("unroll") for (int _i = 0; _i < 2; ++_i) \
;         __builtin_amdgcn_global_load_lds((const unsigned*)((const char*)(gbase) + (voff)[_i]), (PG8_LAS unsigned*)(lds + (bufoff) + ldsw + _i * 8192), 16, 0, 0); } while (0)
; #define PG8_LDA(dst, b, h) do { _Pragma("unroll") for (int m = 0; m < 4; ++m) _Pragma("unroll") for (int k = 0; k < 2; ++k) dst[m][k] = *(const PG8_LAS bf16x8*)(lds + PG8_SA(b, h) + aoff + m * 2048 + k * 1024); } while (0)
; #define PG8_LDB(dst, b, h) do { _Pragma("unroll") for (int n = 0; n < 2; ++n) _Pragma("unroll") for (int k = 0; k < 2; ++k) dst[n][k] = *(const PG8_LAS bf16x8*)(lds + PG8_SB(b, h) + boff + n * 2048 + k * 1024); } while (0)
; #define PG8_MMA(ai, bj, At, Bt) do { __builtin_amdgcn_s_setprio(1); _Pragma("unroll") for (int m = 0; m < 4; ++m) _Pragma("unroll") for (int n = 0; n < 2; ++n) _Pragma("unroll") for (int k = 0; k < 2; ++k) \
;         acc[ai][bj][m][n] = __builtin_amdgcn_mfma_f32_16x16x32_bf16(Bt[n][k], At[m][k], acc[ai][bj][m][n], 0, 0, 0); __builtin_amdgcn_s_setprio(0); } while (0)
; #define PG8_WAIT_V(n) asm volatile("s_waitcnt vmcnt(" #n ")" ::: "memory")
; #define PG8_WAIT_L(n) asm volatile("s_waitcnt lgkmcnt(" #n ")" ::: "memory")
; #define PG8_BAR __builtin_amdgcn_s_barrier()
; #define PG8_SCHED __builtin_amdgcn_sched_barrier(0)
; template <class Epi, class Sched, bool ALIGN_EPI = false, bool SP2 = false>
; __device__ __forceinline__ void gemm_phase(PG8_LAS unsigned char* lds, const Gemm g, const Sched& S, const Epi& E, const int tid_in) {
;     ...
;             PG8_LDB(B0, 1, 0); PG8_LDB(B1, 1, 1); PG8_SCHED; PG8_LDA(At, 1, 0); PG8_STAGE(PG8_SA(0, 1), a2 + hstep, voffA);
;             PG8_WAIT_V(8); PG8_WAIT_L(0); PG8_BAR; PG8_MMA(0, 0, At, B0); PG8_MMA(0, 1, At, B1); PG8_BAR; PG8_SCHED;
	s_add_i32 s59, 0, 0x18000
	s_add_i32 s60, 0, 0x1c000
	v_add_u32_e32 v156, s59, v141
	v_add_u32_e32 v172, s60, v141
	ds_read_b128 v[144:147], v156
	ds_read_b128 v[148:151], v156 offset:1024
	ds_read_b128 v[152:155], v156 offset:2048
	ds_read_b128 v[156:159], v156 offset:3072
	ds_read_b128 v[160:163], v172
	ds_read_b128 v[164:167], v172 offset:1024
	ds_read_b128 v[168:171], v172 offset:2048
	ds_read_b128 v[172:175], v172 offset:3072
	s_add_u32 s10, s10, 0x80000
	s_addc_u32 s11, s11, 0
	s_mov_b32 m0, s23
	v_lshl_add_u64 v[242:243], s[10:11], 0, v[134:135]
	ds_read_b128 v[176:179], v143 offset:32768
	ds_read_b128 v[184:187], v143 offset:33792
	ds_read_b128 v[196:199], v143 offset:34816
	ds_read_b128 v[200:203], v143 offset:35840
	ds_read_b128 v[204:207], v143 offset:36864
	ds_read_b128 v[208:211], v143 offset:37888
	ds_read_b128 v[212:215], v143 offset:38912
	ds_read_b128 v[216:219], v143 offset:39936
	global_load_lds_dwordx4 v[242:243], off
	v_lshl_add_u64 v[242:243], s[10:11], 0, v[132:133]
	s_mov_b32 m0, s34
	s_nop 0
	global_load_lds_dwordx4 v[242:243], off
	s_waitcnt vmcnt(8)
	s_waitcnt lgkmcnt(0)
	s_barrier
	s_waitcnt lgkmcnt(0)
	v_mfma_f32_16x16x32_bf16 v[126:129], v[144:147], v[176:179], v[126:129]
	v_mfma_f32_16x16x32_bf16 v[118:121], v[152:155], v[176:179], v[118:121]
	v_mfma_f32_16x16x32_bf16 v[110:113], v[144:147], v[196:199], v[110:113]
	v_mfma_f32_16x16x32_bf16 v[102:105], v[152:155], v[196:199], v[102:105]
	v_mfma_f32_16x16x32_bf16 v[92:95], v[144:147], v[204:207], v[92:95]
	v_mfma_f32_16x16x32_bf16 v[84:87], v[152:155], v[204:207], v[84:87]
	v_mfma_f32_16x16x32_bf16 v[76:79], v[144:147], v[212:215], v[76:79]
	v_mfma_f32_16x16x32_bf16 v[68:71], v[152:155], v[212:215], v[68:71]
	v_mfma_f32_16x16x32_bf16 v[126:129], v[148:151], v[184:187], v[126:129]
	v_mfma_f32_16x16x32_bf16 v[118:121], v[156:159], v[184:187], v[118:121]
	v_mfma_f32_16x16x32_bf16 v[110:113], v[148:151], v[200:203], v[110:113]
	v_mfma_f32_16x16x32_bf16 v[102:105], v[156:159], v[200:203], v[102:105]
	v_mfma_f32_16x16x32_bf16 v[92:95], v[148:151], v[208:211], v[92:95]
	v_mfma_f32_16x16x32_bf16 v[84:87], v[156:159], v[208:211], v[84:87]
	v_mfma_f32_16x16x32_bf16 v[76:79], v[148:151], v[216:219], v[76:79]
	v_mfma_f32_16x16x32_bf16 v[68:71], v[156:159], v[216:219], v[68:71]
	v_mfma_f32_16x16x32_bf16 v[122:125], v[160:163], v[176:179], v[122:125]
	v_mfma_f32_16x16x32_bf16 v[114:117], v[168:171], v[176:179], v[114:117]
	v_mfma_f32_16x16x32_bf16 v[106:109], v[160:163], v[196:199], v[106:109]
	v_mfma_f32_16x16x32_bf16 v[98:101], v[168:171], v[196:199], v[98:101]
	v_mfma_f32_16x16x32_bf16 v[88:91], v[160:163], v[204:207], v[88:91]
	v_mfma_f32_16x16x32_bf16 v[80:83], v[168:171], v[204:207], v[80:83]
	v_mfma_f32_16x16x32_bf16 v[72:75], v[160:163], v[212:215], v[72:75]
	v_mfma_f32_16x16x32_bf16 v[64:67], v[168:171], v[212:215], v[64:67]
	v_mfma_f32_16x16x32_bf16 v[122:125], v[164:167], v[184:187], v[122:125]
	v_mfma_f32_16x16x32_bf16 v[114:117], v[172:175], v[184:187], v[114:117]
	v_mfma_f32_16x16x32_bf16 v[106:109], v[164:167], v[200:203], v[106:109]
	v_mfma_f32_16x16x32_bf16 v[98:101], v[172:175], v[200:203], v[98:101]
	v_mfma_f32_16x16x32_bf16 v[88:91], v[164:167], v[208:211], v[88:91]
	v_mfma_f32_16x16x32_bf16 v[80:83], v[172:175], v[208:211], v[80:83]
	v_mfma_f32_16x16x32_bf16 v[72:75], v[164:167], v[216:219], v[72:75]
	v_mfma_f32_16x16x32_bf16 v[64:67], v[172:175], v[216:219], v[64:67]
	s_barrier
; #define PG8_STAGE(bufoff, gbase, voff) do { _Pragma("unroll") for (int _i = 0; _i < 2; ++_i) \
;         __builtin_amdgcn_global_load_lds((const unsigned*)((const char*)(gbase) + (voff)[_i]), (PG8_LAS unsigned*)(lds + (bufoff) + ldsw + _i * 8192), 16, 0, 0); } while (0)
; #define PG8_LDA(dst, b, h) do { _Pragma("unroll") for (int m = 0; m < 4; ++m) _Pragma("unroll") for (int k = 0; k < 2; ++k) dst[m][k] = *(const PG8_LAS bf16x8*)(lds + PG8_SA(b, h) + aoff + m * 2048 + k * 1024); } while (0)
; #define PG8_WAIT_V(n) asm volatile("s_waitcnt vmcnt(" #n ")" ::: "memory")
; #define PG8_WAIT_L(n) asm volatile("s_waitcnt lgkmcnt(" #n ")" ::: "memory")
; #define PG8_BAR __builtin_amdgcn_s_barrier()
; template <class Epi, class Sched, bool ALIGN_EPI = false, bool SP2 = false>
; __device__ __forceinline__ void gemm_phase(PG8_LAS unsigned char* lds, const Gemm g, const Sched& S, const Epi& E, const int tid_in) {
;     ...
;         for (int t = 0; t < nt; t += 2) {
;             const bool last = (t == nt - 2);
;             const char* a1 = cA + (size_t)(t + 1) * kstep;
;             const char* a2 = last ? nA : cA + (size_t)(t + 2) * kstep; const char* b2 = last ? nB : cB + (size_t)(t + 2) * kstep;
;             const char* a3 = a2 + kstep; const char* b3 = b2 + kstep;
;             if (last && has_next) S.a_ready(nxt);
;             if constexpr (SP2) {
;             PG8_LDB(B0, 0, 0); PG8_LDB(B1, 0, 1); PG8_SCHED; PG8_LDA(At, 0, 0); PG8_STAGE(PG8_SA(1, 1), a1 + hstep, voffA);
;             PG8_WAIT_V(8); PG8_WAIT_L(0); PG8_BAR; PG8_MMA(0, 0, At, B0); PG8_MMA(0, 1, At, B1); PG8_BAR; PG8_SCHED;
;             PG8_LDA(At, 0, 1); PG8_STAGE(PG8_SB(0, 0), b2, voffB); PG8_STAGE(PG8_SB(0, 1), b2 + hstep, voffB); PG8_STAGE(PG8_SA(0, 0), a2, voffA);
;             PG8_WAIT_V(8); PG8_WAIT_L(0); PG8_BAR; PG8_MMA(1, 0, At, B0); PG8_MMA(1, 1, At, B1); PG8_BAR; PG8_SCHED;
;             PG8_LDB(B0, 1, 0); PG8_LDB(B1, 1, 1); PG8_SCHED; PG8_LDA(At, 1, 0); PG8_STAGE(PG8_SA(0, 1), a2 + hstep, voffA);
;             PG8_WAIT_V(8); PG8_WAIT_L(0); PG8_BAR; PG8_MMA(0, 0, At, B0); PG8_MMA(0, 1, At, B1); PG8_BAR; PG8_SCHED;
;             PG8_LDA(At, 1, 1); PG8_STAGE(PG8_SB(1, 0), b3, voffB); PG8_STAGE(PG8_SB(1, 1), b3 + hstep, voffB); PG8_STAGE(PG8_SA(1, 0), a3, voffA);
;             PG8_WAIT_V(8); PG8_WAIT_L(0); PG8_BAR; PG8_MMA(1, 0, At, B0); PG8_MMA(1, 1, At, B1); PG8_BAR; PG8_SCHED;
	s_add_i32 s10, s59, s19
	v_lshl_add_u64 v[180:181], v[180:181], 0, s[2:3]
	s_mov_b32 m0, s10
	ds_read_b128 v[176:179], v143 offset:49152
	ds_read_b128 v[184:187], v143 offset:50176
	ds_read_b128 v[196:199], v143 offset:51200
	ds_read_b128 v[200:203], v143 offset:52224
	ds_read_b128 v[204:207], v143 offset:53248
	ds_read_b128 v[208:211], v143 offset:54272
	ds_read_b128 v[212:215], v143 offset:55296
	ds_read_b128 v[216:219], v143 offset:56320
	global_load_lds_dwordx4 v[180:181], off
	s_add_i32 m0, s10, 0x2000
	s_add_u32 s8, s8, 0x80080
	v_lshl_add_u64 v[180:181], v[220:221], 0, s[2:3]
	s_addc_u32 s9, s9, 0
	s_add_i32 s10, s60, s19
	global_load_lds_dwordx4 v[180:181], off
	v_lshl_add_u64 v[180:181], s[8:9], 0, v[96:97]
	s_mov_b32 m0, s10
	s_nop 0
	global_load_lds_dwordx4 v[180:181], off
	v_lshl_add_u64 v[180:181], s[8:9], 0, v[130:131]
	s_add_i32 m0, s10, 0x2000
	s_nop 0
	global_load_lds_dwordx4 v[180:181], off
	v_lshl_add_u64 v[180:181], v[222:223], 0, s[2:3]
	s_mov_b32 m0, s46
	s_nop 0
	global_load_lds_dwordx4 v[180:181], off
	v_lshl_add_u64 v[180:181], v[224:225], 0, s[2:3]
	s_mov_b32 m0, s52
	s_nop 0
	global_load_lds_dwordx4 v[180:181], off
	s_waitcnt vmcnt(8)
	s_waitcnt lgkmcnt(0)
	s_barrier
	s_waitcnt lgkmcnt(0)
	v_mfma_f32_16x16x32_bf16 v[60:63], v[144:147], v[176:179], v[60:63]
	v_mfma_f32_16x16x32_bf16 v[52:55], v[152:155], v[176:179], v[52:55]
	v_mfma_f32_16x16x32_bf16 v[44:47], v[144:147], v[196:199], v[44:47]
	v_mfma_f32_16x16x32_bf16 v[36:39], v[152:155], v[196:199], v[36:39]
	v_mfma_f32_16x16x32_bf16 v[28:31], v[144:147], v[204:207], v[28:31]
	v_mfma_f32_16x16x32_bf16 v[20:23], v[152:155], v[204:207], v[20:23]
	v_mfma_f32_16x16x32_bf16 v[12:15], v[144:147], v[212:215], v[12:15]
	v_mfma_f32_16x16x32_bf16 v[4:7], v[152:155], v[212:215], v[4:7]
	v_mfma_f32_16x16x32_bf16 v[60:63], v[148:151], v[184:187], v[60:63]
	v_mfma_f32_16x16x32_bf16 v[52:55], v[156:159], v[184:187], v[52:55]
	v_mfma_f32_16x16x32_bf16 v[44:47], v[148:151], v[200:203], v[44:47]
	v_mfma_f32_16x16x32_bf16 v[36:39], v[156:159], v[200:203], v[36:39]
	v_mfma_f32_16x16x32_bf16 v[28:31], v[148:151], v[208:211], v[28:31]
	v_mfma_f32_16x16x32_bf16 v[20:23], v[156:159], v[208:211], v[20:23]
	v_mfma_f32_16x16x32_bf16 v[12:15], v[148:151], v[216:219], v[12:15]
	v_mfma_f32_16x16x32_bf16 v[4:7], v[156:159], v[216:219], v[4:7]
	v_mfma_f32_16x16x32_bf16 v[56:59], v[160:163], v[176:179], v[56:59]
	v_mfma_f32_16x16x32_bf16 v[48:51], v[168:171], v[176:179], v[48:51]
	v_mfma_f32_16x16x32_bf16 v[40:43], v[160:163], v[196:199], v[40:43]
	v_mfma_f32_16x16x32_bf16 v[32:35], v[168:171], v[196:199], v[32:35]
	v_mfma_f32_16x16x32_bf16 v[24:27], v[160:163], v[204:207], v[24:27]
	v_mfma_f32_16x16x32_bf16 v[16:19], v[168:171], v[204:207], v[16:19]
	v_mfma_f32_16x16x32_bf16 v[8:11], v[160:163], v[212:215], v[8:11]
	v_mfma_f32_16x16x32_bf16 v[0:3], v[168:171], v[212:215], v[0:3]
	v_mfma_f32_16x16x32_bf16 v[56:59], v[164:167], v[184:187], v[56:59]
	v_mfma_f32_16x16x32_bf16 v[48:51], v[172:175], v[184:187], v[48:51]
	v_mfma_f32_16x16x32_bf16 v[40:43], v[164:167], v[200:203], v[40:43]
	v_mfma_f32_16x16x32_bf16 v[32:35], v[172:175], v[200:203], v[32:35]
	v_mfma_f32_16x16x32_bf16 v[24:27], v[164:167], v[208:211], v[24:27]
	v_mfma_f32_16x16x32_bf16 v[16:19], v[172:175], v[208:211], v[16:19]
	v_mfma_f32_16x16x32_bf16 v[8:11], v[164:167], v[216:219], v[8:11]
	v_mfma_f32_16x16x32_bf16 v[0:3], v[172:175], v[216:219], v[0:3]
	s_barrier
	s_add_i32 s58, s58, 2
	s_add_u32 s50, s50, 0x100
	s_addc_u32 s51, s51, 0
	s_add_u32 s56, s56, 0x100
	s_addc_u32 s57, s57, 0
	s_cmp_gt_u32 s58, 29
	s_cbranch_scc0 .LBB0_138
	s_setprio 0
	s_and_b64 vcc, exec, s[36:37]
	s_cbranch_vccz .LBB0_141
	s_barrier

; #define PG8_STAGE(bufoff, gbase, voff) do { _Pragma("unroll") for (int _i = 0; _i < 2; ++_i) \
;         __builtin_amdgcn_global_load_lds((const unsigned*)((const char*)(gbase) + (voff)[_i]), (PG8_LAS unsigned*)(lds + (bufoff) + ldsw + _i * 8192), 16, 0, 0); } while (0)
; #define PG8_LDA(dst, b, h) do { _Pragma("unroll") for (int m = 0; m < 4; ++m) _Pragma("unroll") for (int k = 0; k < 2; ++k) dst[m][k] = *(const PG8_LAS bf16x8*)(lds + PG8_SA(b, h) + aoff + m * 2048 + k * 1024); } while (0)
; #define PG8_LDB(dst, b, h) do { _Pragma("unroll") for (int n = 0; n < 2; ++n) _Pragma("unroll") for (int k = 0; k < 2; ++k) dst[n][k] = *(const PG8_LAS bf16x8*)(lds + PG8_SB(b, h) + boff + n * 2048 + k * 1024); } while (0)
; #define PG8_WAIT_V(n) asm volatile("s_waitcnt vmcnt(" #n ")" ::: "memory")
; #define PG8_WAIT_L(n) asm volatile("s_waitcnt lgkmcnt(" #n ")" ::: "memory")
; #define PG8_BAR __builtin_amdgcn_s_barrier()
; template <class Epi, class Sched, bool ALIGN_EPI = false, bool SP2 = false>
; __device__ __forceinline__ void gemm_phase(PG8_LAS unsigned char* lds, const Gemm g, const Sched& S, const Epi& E, const int tid_in) {
;     ...
;         const bool has_next = S.next(ui + 1, nxt);
;         const char* nA = has_next ? (const char*)g.A + (size_t)nxt.pm * tstep : cA; const char* nB = has_next ? (const char*)g.Bt + (size_t)nxt.pn * tstep : cB;
;         for (int t = 0; t < nt; t += 2) {
;             const bool last = (t == nt - 2);
;             const char* a1 = cA + (size_t)(t + 1) * kstep;
;             const char* a2 = last ? nA : cA + (size_t)(t + 2) * kstep; const char* b2 = last ? nB : cB + (size_t)(t + 2) * kstep;
;             const char* a3 = a2 + kstep; const char* b3 = b2 + kstep;
;             if (last && has_next) S.a_ready(nxt);
;             if constexpr (SP2) {
;             PG8_LDB(B0, 0, 0); PG8_LDB(B1, 0, 1); PG8_SCHED; PG8_LDA(At, 0, 0); PG8_STAGE(PG8_SA(1, 1), a1 + hstep, voffA);
;             PG8_WAIT_V(8); PG8_WAIT_L(0); PG8_BAR; PG8_MMA(0, 0, At, B0); PG8_MMA(0, 1, At, B1); PG8_BAR; PG8_SCHED;
;     ...
; #pragma unroll
;         for (int a = 0; a < 2; ++a)
; #pragma unroll
;             for (int b = 0; b < 2; ++b)
; #pragma unroll
;                 for (int m = 0; m < 4; ++m)
; #pragma unroll
;                     for (int n = 0; n < 2; ++n) acc[a][b][m][n] = (f32x4){0.f, 0.f, 0.f, 0.f};
;         cur = nxt; cA = nA; cB = nB; ++ui;
.LBB0_179:
	s_ashr_i32 s43, s42, 31
	s_lshl_b64 s[12:13], s[42:43], 20
	v_readlane_b32 s44, v255, 4
	v_readlane_b32 s45, v255, 5
	s_add_u32 s44, s44, s12
	s_addc_u32 s45, s45, s13
	s_and_b64 s[12:13], s[38:39], exec
	s_cselect_b32 s12, s45, s11
	s_cselect_b32 s13, s44, s10
	s_ashr_i32 s41, s40, 31
	s_lshl_b64 s[48:49], s[40:41], 20
	s_add_u32 s48, s14, s48
	s_addc_u32 s49, s15, s49
	s_and_b64 s[50:51], s[38:39], exec
	s_cselect_b32 s41, s49, s9
	s_cselect_b32 s43, s48, s8
	s_add_u32 s50, s10, 0x80080
	s_addc_u32 s51, s11, 0
	s_add_u32 s58, s8, 0x100
	v_mov_b32_e32 v0, 0
	s_addc_u32 s59, s9, 0
	s_mov_b32 s60, -2
	v_mov_b32_e32 v1, v0
	v_mov_b32_e32 v2, v0
	v_mov_b32_e32 v3, v0
	v_mov_b32_e32 v4, v0
	v_mov_b32_e32 v5, v0
	v_mov_b32_e32 v6, v0
	v_mov_b32_e32 v7, v0
	v_mov_b32_e32 v8, v0
	v_mov_b32_e32 v9, v0
	v_mov_b32_e32 v10, v0
	v_mov_b32_e32 v11, v0
	v_mov_b32_e32 v16, v0
	v_mov_b32_e32 v17, v0
	v_mov_b32_e32 v18, v0
	v_mov_b32_e32 v19, v0
	v_mov_b32_e32 v24, v0
	v_mov_b32_e32 v25, v0
	v_mov_b32_e32 v26, v0
	v_mov_b32_e32 v27, v0
	v_mov_b32_e32 v32, v0
	v_mov_b32_e32 v33, v0
	v_mov_b32_e32 v34, v0
	v_mov_b32_e32 v35, v0
	v_mov_b32_e32 v40, v0
	v_mov_b32_e32 v41, v0
	v_mov_b32_e32 v42, v0
	v_mov_b32_e32 v43, v0
	v_mov_b32_e32 v48, v0
	v_mov_b32_e32 v49, v0
	v_mov_b32_e32 v50, v0
	v_mov_b32_e32 v51, v0
	v_mov_b32_e32 v12, v0
	v_mov_b32_e32 v13, v0
	v_mov_b32_e32 v14, v0
	v_mov_b32_e32 v15, v0
	v_mov_b32_e32 v20, v0
	v_mov_b32_e32 v21, v0
	v_mov_b32_e32 v22, v0
	v_mov_b32_e32 v23, v0
	v_mov_b32_e32 v28, v0
	v_mov_b32_e32 v29, v0
	v_mov_b32_e32 v30, v0
	v_mov_b32_e32 v31, v0
	v_mov_b32_e32 v36, v0
	v_mov_b32_e32 v37, v0
	v_mov_b32_e32 v38, v0
	v_mov_b32_e32 v39, v0
	v_mov_b32_e32 v44, v0
	v_mov_b32_e32 v45, v0
	v_mov_b32_e32 v46, v0
	v_mov_b32_e32 v47, v0
	v_mov_b32_e32 v52, v0
	v_mov_b32_e32 v53, v0
	v_mov_b32_e32 v54, v0
	v_mov_b32_e32 v55, v0
	v_mov_b32_e32 v56, v0
	v_mov_b32_e32 v57, v0
	v_mov_b32_e32 v58, v0
	v_mov_b32_e32 v59, v0
	v_mov_b32_e32 v60, v0
	v_mov_b32_e32 v61, v0
	v_mov_b32_e32 v62, v0
	v_mov_b32_e32 v63, v0
	v_mov_b32_e32 v64, v0
	v_mov_b32_e32 v65, v0
	v_mov_b32_e32 v66, v0
	v_mov_b32_e32 v67, v0
	v_mov_b32_e32 v68, v0
	v_mov_b32_e32 v69, v0
	v_mov_b32_e32 v70, v0
	v_mov_b32_e32 v71, v0
	v_mov_b32_e32 v80, v0
	v_mov_b32_e32 v81, v0
	v_mov_b32_e32 v82, v0
	v_mov_b32_e32 v83, v0
	v_mov_b32_e32 v84, v0
	v_mov_b32_e32 v85, v0
	v_mov_b32_e32 v86, v0
	v_mov_b32_e32 v87, v0
	v_mov_b32_e32 v98, v0
	v_mov_b32_e32 v99, v0
	v_mov_b32_e32 v100, v0
	v_mov_b32_e32 v101, v0
	v_mov_b32_e32 v102, v0
	v_mov_b32_e32 v103, v0
	v_mov_b32_e32 v104, v0
	v_mov_b32_e32 v105, v0
	v_mov_b32_e32 v130, v0
	v_mov_b32_e32 v131, v0
	v_mov_b32_e32 v132, v0
	v_mov_b32_e32 v133, v0
	v_mov_b32_e32 v134, v0
	v_mov_b32_e32 v135, v0
	v_mov_b32_e32 v136, v0
	v_mov_b32_e32 v137, v0
	v_mov_b32_e32 v72, v0
	v_mov_b32_e32 v73, v0
	v_mov_b32_e32 v74, v0
	v_mov_b32_e32 v75, v0
	v_mov_b32_e32 v76, v0
	v_mov_b32_e32 v77, v0
	v_mov_b32_e32 v78, v0
	v_mov_b32_e32 v79, v0
	v_mov_b32_e32 v88, v0
	v_mov_b32_e32 v89, v0
	v_mov_b32_e32 v90, v0
	v_mov_b32_e32 v91, v0
	v_mov_b32_e32 v92, v0
	v_mov_b32_e32 v93, v0
	v_mov_b32_e32 v94, v0
	v_mov_b32_e32 v95, v0
	v_mov_b32_e32 v106, v0
	v_mov_b32_e32 v107, v0
	v_mov_b32_e32 v108, v0
	v_mov_b32_e32 v109, v0
	v_mov_b32_e32 v110, v0
	v_mov_b32_e32 v111, v0
	v_mov_b32_e32 v112, v0
	v_mov_b32_e32 v113, v0
	v_mov_b32_e32 v138, v0
	v_mov_b32_e32 v139, v0
	v_mov_b32_e32 v140, v0
	v_mov_b32_e32 v141, v0
	v_mov_b32_e32 v142, v0
	v_mov_b32_e32 v143, v0
	v_mov_b32_e32 v144, v0
	v_mov_b32_e32 v145, v0
	v_readfirstlane_b32 s70, v241
	s_nop 3
	s_lshr_b32 s70, s70, 6
	s_cmp_ge_u32 s70, 4
	s_cbranch_scc0 .Lprio_done_180
	s_setprio 1
.Lprio_done_180:
.LBB0_180:
	s_add_u32 s8, s50, 0xfff80080
	s_addc_u32 s9, s51, -1
	s_add_i32 s61, 0, 0x10000
	s_cmp_eq_u32 s60, 28
	s_cselect_b32 s11, s12, s9
	s_cselect_b32 s10, s13, s8
	s_cselect_b32 s9, s41, s59
	s_cselect_b32 s8, s43, s58
	s_add_i32 s64, 0, 0x14000
	v_add_u32_e32 v126, s61, v163
	v_add_u32_e32 v160, s64, v163
	ds_read_b128 v[114:117], v126
	ds_read_b128 v[118:121], v126 offset:1024
	ds_read_b128 v[122:125], v126 offset:2048
	ds_read_b128 v[126:129], v126 offset:3072
	ds_read_b128 v[156:159], v160
	ds_read_b128 v[166:169], v160 offset:1024
	ds_read_b128 v[170:173], v160 offset:2048
	ds_read_b128 v[174:177], v160 offset:3072
	v_lshl_add_u64 v[160:161], s[50:51], 0, v[152:153]
	s_add_i32 m0, s20, 0xc000
	ds_read_b128 v[178:181], v165
	ds_read_b128 v[184:187], v165 offset:1024
	ds_read_b128 v[196:199], v165 offset:2048
	ds_read_b128 v[200:203], v165 offset:3072
	ds_read_b128 v[204:207], v165 offset:4096
	ds_read_b128 v[208:211], v165 offset:5120
	ds_read_b128 v[212:215], v165 offset:6144
	ds_read_b128 v[216:219], v165 offset:7168
	global_load_lds_dwordx4 v[160:161], off
	v_lshl_add_u64 v[160:161], s[50:51], 0, v[154:155]
	s_add_i32 m0, s20, 0xe000
	s_nop 0
	global_load_lds_dwordx4 v[160:161], off
	s_waitcnt vmcnt(8)
	s_waitcnt lgkmcnt(0)
	s_barrier
; #define PG8_STAGE(bufoff, gbase, voff) do { _Pragma("unroll") for (int _i = 0; _i < 2; ++_i) \
;         __builtin_amdgcn_global_load_lds((const unsigned*)((const char*)(gbase) + (voff)[_i]), (PG8_LAS unsigned*)(lds + (bufoff) + ldsw + _i * 8192), 16, 0, 0); } while (0)
; #define PG8_LDA(dst, b, h) do { _Pragma("unroll") for (int m = 0; m < 4; ++m) _Pragma("unroll") for (int k = 0; k < 2; ++k) dst[m][k] = *(const PG8_LAS bf16x8*)(lds + PG8_SA(b, h) + aoff + m * 2048 + k * 1024); } while (0)
; #define PG8_LDB(dst, b, h) do { _Pragma("unroll") for (int n = 0; n < 2; ++n) _Pragma("unroll") for (int k = 0; k < 2; ++k) dst[n][k] = *(const PG8_LAS bf16x8*)(lds + PG8_SB(b, h) + boff + n * 2048 + k * 1024); } while (0)
; #define PG8_MMA(ai, bj, At, Bt) do { __builtin_amdgcn_s_setprio(1); _Pragma("unroll") for (int m = 0; m < 4; ++m) _Pragma("unroll") for (int n = 0; n < 2; ++n) _Pragma("unroll") for (int k = 0; k < 2; ++k) \
;         acc[ai][bj][m][n] = __builtin_amdgcn_mfma_f32_16x16x32_bf16(Bt[n][k], At[m][k], acc[ai][bj][m][n], 0, 0, 0); __builtin_amdgcn_s_setprio(0); } while (0)
; #define PG8_WAIT_V(n) asm volatile("s_waitcnt vmcnt(" #n ")" ::: "memory")
; #define PG8_WAIT_L(n) asm volatile("s_waitcnt lgkmcnt(" #n ")" ::: "memory")
; #define PG8_BAR __builtin_amdgcn_s_barrier()
; #define PG8_SCHED __builtin_amdgcn_sched_barrier(0)
; template <class Epi, class Sched, bool ALIGN_EPI = false, bool SP2 = false>
; __device__ __forceinline__ void gemm_phase(PG8_LAS unsigned char* lds, const Gemm g, const Sched& S, const Epi& E, const int tid_in) {
;     ...
;             PG8_LDB(B0, 0, 0); PG8_LDB(B1, 0, 1); PG8_SCHED; PG8_LDA(At, 0, 0); PG8_STAGE(PG8_SA(1, 1), a1 + hstep, voffA);
;             PG8_WAIT_V(8); PG8_WAIT_L(0); PG8_BAR; PG8_MMA(0, 0, At, B0); PG8_MMA(0, 1, At, B1); PG8_BAR; PG8_SCHED;
;             PG8_LDA(At, 0, 1); PG8_STAGE(PG8_SB(0, 0), b2, voffB); PG8_STAGE(PG8_SB(0, 1), b2 + hstep, voffB); PG8_STAGE(PG8_SA(0, 0), a2, voffA);
;             PG8_WAIT_V(8); PG8_WAIT_L(0); PG8_BAR; PG8_MMA(1, 0, At, B0); PG8_MMA(1, 1, At, B1); PG8_BAR; PG8_SCHED;
	s_waitcnt lgkmcnt(0)
	v_mfma_f32_16x16x32_bf16 v[142:145], v[114:117], v[178:181], v[142:145]
	v_mfma_f32_16x16x32_bf16 v[138:141], v[122:125], v[178:181], v[138:141]
	v_mfma_f32_16x16x32_bf16 v[110:113], v[114:117], v[196:199], v[110:113]
	v_mfma_f32_16x16x32_bf16 v[106:109], v[122:125], v[196:199], v[106:109]
	v_mfma_f32_16x16x32_bf16 v[92:95], v[114:117], v[204:207], v[92:95]
	v_mfma_f32_16x16x32_bf16 v[88:91], v[122:125], v[204:207], v[88:91]
	v_mfma_f32_16x16x32_bf16 v[76:79], v[114:117], v[212:215], v[76:79]
	v_mfma_f32_16x16x32_bf16 v[72:75], v[122:125], v[212:215], v[72:75]
	v_mfma_f32_16x16x32_bf16 v[142:145], v[118:121], v[184:187], v[142:145]
	v_mfma_f32_16x16x32_bf16 v[138:141], v[126:129], v[184:187], v[138:141]
	v_mfma_f32_16x16x32_bf16 v[110:113], v[118:121], v[200:203], v[110:113]
	v_mfma_f32_16x16x32_bf16 v[106:109], v[126:129], v[200:203], v[106:109]
	v_mfma_f32_16x16x32_bf16 v[92:95], v[118:121], v[208:211], v[92:95]
	v_mfma_f32_16x16x32_bf16 v[88:91], v[126:129], v[208:211], v[88:91]
	v_mfma_f32_16x16x32_bf16 v[76:79], v[118:121], v[216:219], v[76:79]
	v_mfma_f32_16x16x32_bf16 v[72:75], v[126:129], v[216:219], v[72:75]
	v_mfma_f32_16x16x32_bf16 v[134:137], v[156:159], v[178:181], v[134:137]
	v_mfma_f32_16x16x32_bf16 v[130:133], v[170:173], v[178:181], v[130:133]
	v_mfma_f32_16x16x32_bf16 v[102:105], v[156:159], v[196:199], v[102:105]
	v_mfma_f32_16x16x32_bf16 v[98:101], v[170:173], v[196:199], v[98:101]
	v_mfma_f32_16x16x32_bf16 v[84:87], v[156:159], v[204:207], v[84:87]
	v_mfma_f32_16x16x32_bf16 v[80:83], v[170:173], v[204:207], v[80:83]
	v_mfma_f32_16x16x32_bf16 v[68:71], v[156:159], v[212:215], v[68:71]
	v_mfma_f32_16x16x32_bf16 v[64:67], v[170:173], v[212:215], v[64:67]
	v_mfma_f32_16x16x32_bf16 v[134:137], v[166:169], v[184:187], v[134:137]
	v_mfma_f32_16x16x32_bf16 v[130:133], v[174:177], v[184:187], v[130:133]
	v_mfma_f32_16x16x32_bf16 v[102:105], v[166:169], v[200:203], v[102:105]
	v_mfma_f32_16x16x32_bf16 v[98:101], v[174:177], v[200:203], v[98:101]
	v_mfma_f32_16x16x32_bf16 v[84:87], v[166:169], v[208:211], v[84:87]
	v_mfma_f32_16x16x32_bf16 v[80:83], v[174:177], v[208:211], v[80:83]
	v_mfma_f32_16x16x32_bf16 v[68:71], v[166:169], v[216:219], v[68:71]
	v_mfma_f32_16x16x32_bf16 v[64:67], v[174:177], v[216:219], v[64:67]
	s_barrier
	s_add_i32 s61, s61, s19
	v_lshl_add_u64 v[160:161], s[8:9], 0, v[96:97]
	s_mov_b32 m0, s61
	ds_read_b128 v[178:181], v165 offset:16384
	ds_read_b128 v[184:187], v165 offset:17408
	ds_read_b128 v[196:199], v165 offset:18432
	ds_read_b128 v[200:203], v165 offset:19456
	ds_read_b128 v[204:207], v165 offset:20480
	ds_read_b128 v[208:211], v165 offset:21504
	ds_read_b128 v[212:215], v165 offset:22528
	ds_read_b128 v[216:219], v165 offset:23552
	global_load_lds_dwordx4 v[160:161], off
	s_add_i32 m0, s61, 0x2000
	s_add_u32 s62, s8, 0x80000
	v_lshl_add_u64 v[220:221], s[8:9], 0, v[146:147]
	s_addc_u32 s63, s9, 0
	s_add_i32 s61, s64, s19
	global_load_lds_dwordx4 v[220:221], off
	v_lshl_add_u64 v[222:223], s[62:63], 0, v[96:97]
	s_mov_b32 m0, s61
	v_lshl_add_u64 v[224:225], s[10:11], 0, v[148:149]
	global_load_lds_dwordx4 v[222:223], off
	v_lshl_add_u64 v[222:223], s[62:63], 0, v[146:147]
	s_add_i32 m0, s61, 0x2000
	s_nop 0
	global_load_lds_dwordx4 v[222:223], off
	v_lshl_add_u64 v[222:223], s[10:11], 0, v[150:151]
	s_mov_b32 m0, s20
	s_nop 0
	global_load_lds_dwordx4 v[222:223], off
	s_mov_b32 m0, s22
	s_nop 0
	global_load_lds_dwordx4 v[224:225], off
	s_waitcnt vmcnt(8)
	s_waitcnt lgkmcnt(0)
	s_barrier
	s_waitcnt lgkmcnt(0)
	v_mfma_f32_16x16x32_bf16 v[60:63], v[114:117], v[178:181], v[60:63]
	v_mfma_f32_16x16x32_bf16 v[56:59], v[122:125], v[178:181], v[56:59]
	v_mfma_f32_16x16x32_bf16 v[52:55], v[114:117], v[196:199], v[52:55]
	v_mfma_f32_16x16x32_bf16 v[44:47], v[122:125], v[196:199], v[44:47]
	v_mfma_f32_16x16x32_bf16 v[36:39], v[114:117], v[204:207], v[36:39]
	v_mfma_f32_16x16x32_bf16 v[28:31], v[122:125], v[204:207], v[28:31]
	v_mfma_f32_16x16x32_bf16 v[20:23], v[114:117], v[212:215], v[20:23]
	v_mfma_f32_16x16x32_bf16 v[12:15], v[122:125], v[212:215], v[12:15]
	v_mfma_f32_16x16x32_bf16 v[60:63], v[118:121], v[184:187], v[60:63]
	v_mfma_f32_16x16x32_bf16 v[56:59], v[126:129], v[184:187], v[56:59]
	v_mfma_f32_16x16x32_bf16 v[52:55], v[118:121], v[200:203], v[52:55]
	v_mfma_f32_16x16x32_bf16 v[44:47], v[126:129], v[200:203], v[44:47]
	v_mfma_f32_16x16x32_bf16 v[36:39], v[118:121], v[208:211], v[36:39]
	v_mfma_f32_16x16x32_bf16 v[28:31], v[126:129], v[208:211], v[28:31]
	v_mfma_f32_16x16x32_bf16 v[20:23], v[118:121], v[216:219], v[20:23]
	v_mfma_f32_16x16x32_bf16 v[12:15], v[126:129], v[216:219], v[12:15]
	v_mfma_f32_16x16x32_bf16 v[48:51], v[156:159], v[178:181], v[48:51]
	v_mfma_f32_16x16x32_bf16 v[40:43], v[170:173], v[178:181], v[40:43]
	v_mfma_f32_16x16x32_bf16 v[32:35], v[156:159], v[196:199], v[32:35]
	v_mfma_f32_16x16x32_bf16 v[24:27], v[170:173], v[196:199], v[24:27]
	v_mfma_f32_16x16x32_bf16 v[16:19], v[156:159], v[204:207], v[16:19]
	v_mfma_f32_16x16x32_bf16 v[8:11], v[170:173], v[204:207], v[8:11]
	v_mfma_f32_16x16x32_bf16 v[4:7], v[156:159], v[212:215], v[4:7]
	v_mfma_f32_16x16x32_bf16 v[0:3], v[170:173], v[212:215], v[0:3]
	v_mfma_f32_16x16x32_bf16 v[48:51], v[166:169], v[184:187], v[48:51]
	v_mfma_f32_16x16x32_bf16 v[40:43], v[174:177], v[184:187], v[40:43]
	v_mfma_f32_16x16x32_bf16 v[32:35], v[166:169], v[200:203], v[32:35]
	v_mfma_f32_16x16x32_bf16 v[24:27], v[174:177], v[200:203], v[24:27]
	v_mfma_f32_16x16x32_bf16 v[16:19], v[166:169], v[208:211], v[16:19]
	v_mfma_f32_16x16x32_bf16 v[8:11], v[174:177], v[208:211], v[8:11]
	v_mfma_f32_16x16x32_bf16 v[4:7], v[166:169], v[216:219], v[4:7]
	v_mfma_f32_16x16x32_bf16 v[0:3], v[174:177], v[216:219], v[0:3]
	s_barrier
; #define PG8_STAGE(bufoff, gbase, voff) do { _Pragma("unroll") for (int _i = 0; _i < 2; ++_i) \
;         __builtin_amdgcn_global_load_lds((const unsigned*)((const char*)(gbase) + (voff)[_i]), (PG8_LAS unsigned*)(lds + (bufoff) + ldsw + _i * 8192), 16, 0, 0); } while (0)
; #define PG8_LDA(dst, b, h) do { _Pragma("unroll") for (int m = 0; m < 4; ++m) _Pragma("unroll") for (int k = 0; k < 2; ++k) dst[m][k] = *(const PG8_LAS bf16x8*)(lds + PG8_SA(b, h) + aoff + m * 2048 + k * 1024); } while (0)
; #define PG8_LDB(dst, b, h) do { _Pragma("unroll") for (int n = 0; n < 2; ++n) _Pragma("unroll") for (int k = 0; k < 2; ++k) dst[n][k] = *(const PG8_LAS bf16x8*)(lds + PG8_SB(b, h) + boff + n * 2048 + k * 1024); } while (0)
; #define PG8_MMA(ai, bj, At, Bt) do { __builtin_amdgcn_s_setprio(1); _Pragma("unroll") for (int m = 0; m < 4; ++m) _Pragma("unroll") for (int n = 0; n < 2; ++n) _Pragma("unroll") for (int k = 0; k < 2; ++k) \
;         acc[ai][bj][m][n] = __builtin_amdgcn_mfma_f32_16x16x32_bf16(Bt[n][k], At[m][k], acc[ai][bj][m][n], 0, 0, 0); __builtin_amdgcn_s_setprio(0); } while (0)
; #define PG8_WAIT_V(n) asm volatile("s_waitcnt vmcnt(" #n ")" ::: "memory")
; #define PG8_WAIT_L(n) asm volatile("s_waitcnt lgkmcnt(" #n ")" ::: "memory")
; #define PG8_BAR __builtin_amdgcn_s_barrier()
; #define PG8_SCHED __builtin_amdgcn_sched_barrier(0)
; template <class Epi, class Sched, bool ALIGN_EPI = false, bool SP2 = false>
; __device__ __forceinline__ void gemm_phase(PG8_LAS unsigned char* lds, const Gemm g, const Sched& S, const Epi& E, const int tid_in) {
;     ...
;             PG8_LDB(B0, 1, 0); PG8_LDB(B1, 1, 1); PG8_SCHED; PG8_LDA(At, 1, 0); PG8_STAGE(PG8_SA(0, 1), a2 + hstep, voffA);
;             PG8_WAIT_V(8); PG8_WAIT_L(0); PG8_BAR; PG8_MMA(0, 0, At, B0); PG8_MMA(0, 1, At, B1); PG8_BAR; PG8_SCHED;
	s_add_i32 s61, 0, 0x18000
	s_add_i32 s62, 0, 0x1c000
	v_add_u32_e32 v126, s61, v163
	v_add_u32_e32 v174, s62, v163
	ds_read_b128 v[114:117], v126
	ds_read_b128 v[118:121], v126 offset:1024
	ds_read_b128 v[122:125], v126 offset:2048
	ds_read_b128 v[126:129], v126 offset:3072
	ds_read_b128 v[156:159], v174
	ds_read_b128 v[166:169], v174 offset:1024
	ds_read_b128 v[170:173], v174 offset:2048
	ds_read_b128 v[174:177], v174 offset:3072
	s_add_u32 s10, s10, 0x80000
	s_addc_u32 s11, s11, 0
	s_mov_b32 m0, s23
	v_lshl_add_u64 v[242:243], s[10:11], 0, v[150:151]
	ds_read_b128 v[178:181], v165 offset:32768
	ds_read_b128 v[184:187], v165 offset:33792
	ds_read_b128 v[196:199], v165 offset:34816
	ds_read_b128 v[200:203], v165 offset:35840
	ds_read_b128 v[204:207], v165 offset:36864
	ds_read_b128 v[208:211], v165 offset:37888
	ds_read_b128 v[212:215], v165 offset:38912
	ds_read_b128 v[216:219], v165 offset:39936
	global_load_lds_dwordx4 v[242:243], off
	v_lshl_add_u64 v[242:243], s[10:11], 0, v[148:149]
	s_mov_b32 m0, s34
	s_nop 0
	global_load_lds_dwordx4 v[242:243], off
	s_waitcnt vmcnt(8)
	s_waitcnt lgkmcnt(0)
	s_barrier
	s_waitcnt lgkmcnt(0)
	v_mfma_f32_16x16x32_bf16 v[142:145], v[114:117], v[178:181], v[142:145]
	v_mfma_f32_16x16x32_bf16 v[138:141], v[122:125], v[178:181], v[138:141]
	v_mfma_f32_16x16x32_bf16 v[110:113], v[114:117], v[196:199], v[110:113]
	v_mfma_f32_16x16x32_bf16 v[106:109], v[122:125], v[196:199], v[106:109]
	v_mfma_f32_16x16x32_bf16 v[92:95], v[114:117], v[204:207], v[92:95]
	v_mfma_f32_16x16x32_bf16 v[88:91], v[122:125], v[204:207], v[88:91]
	v_mfma_f32_16x16x32_bf16 v[76:79], v[114:117], v[212:215], v[76:79]
	v_mfma_f32_16x16x32_bf16 v[72:75], v[122:125], v[212:215], v[72:75]
	v_mfma_f32_16x16x32_bf16 v[142:145], v[118:121], v[184:187], v[142:145]
	v_mfma_f32_16x16x32_bf16 v[138:141], v[126:129], v[184:187], v[138:141]
	v_mfma_f32_16x16x32_bf16 v[110:113], v[118:121], v[200:203], v[110:113]
	v_mfma_f32_16x16x32_bf16 v[106:109], v[126:129], v[200:203], v[106:109]
	v_mfma_f32_16x16x32_bf16 v[92:95], v[118:121], v[208:211], v[92:95]
	v_mfma_f32_16x16x32_bf16 v[88:91], v[126:129], v[208:211], v[88:91]
	v_mfma_f32_16x16x32_bf16 v[76:79], v[118:121], v[216:219], v[76:79]
	v_mfma_f32_16x16x32_bf16 v[72:75], v[126:129], v[216:219], v[72:75]
	v_mfma_f32_16x16x32_bf16 v[134:137], v[156:159], v[178:181], v[134:137]
	v_mfma_f32_16x16x32_bf16 v[130:133], v[170:173], v[178:181], v[130:133]
	v_mfma_f32_16x16x32_bf16 v[102:105], v[156:159], v[196:199], v[102:105]
	v_mfma_f32_16x16x32_bf16 v[98:101], v[170:173], v[196:199], v[98:101]
	v_mfma_f32_16x16x32_bf16 v[84:87], v[156:159], v[204:207], v[84:87]
	v_mfma_f32_16x16x32_bf16 v[80:83], v[170:173], v[204:207], v[80:83]
	v_mfma_f32_16x16x32_bf16 v[68:71], v[156:159], v[212:215], v[68:71]
	v_mfma_f32_16x16x32_bf16 v[64:67], v[170:173], v[212:215], v[64:67]
	v_mfma_f32_16x16x32_bf16 v[134:137], v[166:169], v[184:187], v[134:137]
	v_mfma_f32_16x16x32_bf16 v[130:133], v[174:177], v[184:187], v[130:133]
	v_mfma_f32_16x16x32_bf16 v[102:105], v[166:169], v[200:203], v[102:105]
	v_mfma_f32_16x16x32_bf16 v[98:101], v[174:177], v[200:203], v[98:101]
	v_mfma_f32_16x16x32_bf16 v[84:87], v[166:169], v[208:211], v[84:87]
	v_mfma_f32_16x16x32_bf16 v[80:83], v[174:177], v[208:211], v[80:83]
	v_mfma_f32_16x16x32_bf16 v[68:71], v[166:169], v[216:219], v[68:71]
	v_mfma_f32_16x16x32_bf16 v[64:67], v[174:177], v[216:219], v[64:67]
	s_barrier
; #define PG8_STAGE(bufoff, gbase, voff) do { _Pragma("unroll") for (int _i = 0; _i < 2; ++_i) \
;         __builtin_amdgcn_global_load_lds((const unsigned*)((const char*)(gbase) + (voff)[_i]), (PG8_LAS unsigned*)(lds + (bufoff) + ldsw + _i * 8192), 16, 0, 0); } while (0)
; #define PG8_LDA(dst, b, h) do { _Pragma("unroll") for (int m = 0; m < 4; ++m) _Pragma("unroll") for (int k = 0; k < 2; ++k) dst[m][k] = *(const PG8_LAS bf16x8*)(lds + PG8_SA(b, h) + aoff + m * 2048 + k * 1024); } while (0)
; #define PG8_WAIT_V(n) asm volatile("s_waitcnt vmcnt(" #n ")" ::: "memory")
; #define PG8_WAIT_L(n) asm volatile("s_waitcnt lgkmcnt(" #n ")" ::: "memory")
; #define PG8_BAR __builtin_amdgcn_s_barrier()
; template <class Epi, class Sched, bool ALIGN_EPI = false, bool SP2 = false>
; __device__ __forceinline__ void gemm_phase(PG8_LAS unsigned char* lds, const Gemm g, const Sched& S, const Epi& E, const int tid_in) {
;     ...
;         for (int t = 0; t < nt; t += 2) {
;             const bool last = (t == nt - 2);
;             const char* a1 = cA + (size_t)(t + 1) * kstep;
;             const char* a2 = last ? nA : cA + (size_t)(t + 2) * kstep; const char* b2 = last ? nB : cB + (size_t)(t + 2) * kstep;
;             const char* a3 = a2 + kstep; const char* b3 = b2 + kstep;
;             if (last && has_next) S.a_ready(nxt);
;             if constexpr (SP2) {
;             PG8_LDB(B0, 0, 0); PG8_LDB(B1, 0, 1); PG8_SCHED; PG8_LDA(At, 0, 0); PG8_STAGE(PG8_SA(1, 1), a1 + hstep, voffA);
;             PG8_WAIT_V(8); PG8_WAIT_L(0); PG8_BAR; PG8_MMA(0, 0, At, B0); PG8_MMA(0, 1, At, B1); PG8_BAR; PG8_SCHED;
;             PG8_LDA(At, 0, 1); PG8_STAGE(PG8_SB(0, 0), b2, voffB); PG8_STAGE(PG8_SB(0, 1), b2 + hstep, voffB); PG8_STAGE(PG8_SA(0, 0), a2, voffA);
;             PG8_WAIT_V(8); PG8_WAIT_L(0); PG8_BAR; PG8_MMA(1, 0, At, B0); PG8_MMA(1, 1, At, B1); PG8_BAR; PG8_SCHED;
;             PG8_LDB(B0, 1, 0); PG8_LDB(B1, 1, 1); PG8_SCHED; PG8_LDA(At, 1, 0); PG8_STAGE(PG8_SA(0, 1), a2 + hstep, voffA);
;             PG8_WAIT_V(8); PG8_WAIT_L(0); PG8_BAR; PG8_MMA(0, 0, At, B0); PG8_MMA(0, 1, At, B1); PG8_BAR; PG8_SCHED;
;             PG8_LDA(At, 1, 1); PG8_STAGE(PG8_SB(1, 0), b3, voffB); PG8_STAGE(PG8_SB(1, 1), b3 + hstep, voffB); PG8_STAGE(PG8_SA(1, 0), a3, voffA);
;             PG8_WAIT_V(8); PG8_WAIT_L(0); PG8_BAR; PG8_MMA(1, 0, At, B0); PG8_MMA(1, 1, At, B1); PG8_BAR; PG8_SCHED;
	s_add_i32 s10, s61, s19
	v_lshl_add_u64 v[160:161], v[160:161], 0, s[2:3]
	s_mov_b32 m0, s10
	ds_read_b128 v[178:181], v165 offset:49152
	ds_read_b128 v[184:187], v165 offset:50176
	ds_read_b128 v[196:199], v165 offset:51200
	ds_read_b128 v[200:203], v165 offset:52224
	ds_read_b128 v[204:207], v165 offset:53248
	ds_read_b128 v[208:211], v165 offset:54272
	ds_read_b128 v[212:215], v165 offset:55296
	ds_read_b128 v[216:219], v165 offset:56320
	global_load_lds_dwordx4 v[160:161], off
	s_add_i32 m0, s10, 0x2000
	s_add_u32 s8, s8, 0x80080
	v_lshl_add_u64 v[160:161], v[220:221], 0, s[2:3]
	s_addc_u32 s9, s9, 0
	s_add_i32 s10, s62, s19
	global_load_lds_dwordx4 v[160:161], off
	v_lshl_add_u64 v[160:161], s[8:9], 0, v[96:97]
	s_mov_b32 m0, s10
	s_nop 0
	global_load_lds_dwordx4 v[160:161], off
	v_lshl_add_u64 v[160:161], s[8:9], 0, v[146:147]
	s_add_i32 m0, s10, 0x2000
	s_nop 0
	global_load_lds_dwordx4 v[160:161], off
	v_lshl_add_u64 v[160:161], v[222:223], 0, s[2:3]
	s_mov_b32 m0, s53
	s_nop 0
	global_load_lds_dwordx4 v[160:161], off
	v_lshl_add_u64 v[160:161], v[224:225], 0, s[2:3]
	s_mov_b32 m0, s54
	s_nop 0
	global_load_lds_dwordx4 v[160:161], off
	s_waitcnt vmcnt(8)
	s_waitcnt lgkmcnt(0)
	s_barrier
	s_waitcnt lgkmcnt(0)
	v_mfma_f32_16x16x32_bf16 v[60:63], v[114:117], v[178:181], v[60:63]
	v_mfma_f32_16x16x32_bf16 v[56:59], v[122:125], v[178:181], v[56:59]
	v_mfma_f32_16x16x32_bf16 v[52:55], v[114:117], v[196:199], v[52:55]
	v_mfma_f32_16x16x32_bf16 v[44:47], v[122:125], v[196:199], v[44:47]
	v_mfma_f32_16x16x32_bf16 v[36:39], v[114:117], v[204:207], v[36:39]
	v_mfma_f32_16x16x32_bf16 v[28:31], v[122:125], v[204:207], v[28:31]
	v_mfma_f32_16x16x32_bf16 v[20:23], v[114:117], v[212:215], v[20:23]
	v_mfma_f32_16x16x32_bf16 v[12:15], v[122:125], v[212:215], v[12:15]
	v_mfma_f32_16x16x32_bf16 v[60:63], v[118:121], v[184:187], v[60:63]
	v_mfma_f32_16x16x32_bf16 v[56:59], v[126:129], v[184:187], v[56:59]
	v_mfma_f32_16x16x32_bf16 v[52:55], v[118:121], v[200:203], v[52:55]
	v_mfma_f32_16x16x32_bf16 v[44:47], v[126:129], v[200:203], v[44:47]
	v_mfma_f32_16x16x32_bf16 v[36:39], v[118:121], v[208:211], v[36:39]
	v_mfma_f32_16x16x32_bf16 v[28:31], v[126:129], v[208:211], v[28:31]
	v_mfma_f32_16x16x32_bf16 v[20:23], v[118:121], v[216:219], v[20:23]
	v_mfma_f32_16x16x32_bf16 v[12:15], v[126:129], v[216:219], v[12:15]
	v_mfma_f32_16x16x32_bf16 v[48:51], v[156:159], v[178:181], v[48:51]
	v_mfma_f32_16x16x32_bf16 v[40:43], v[170:173], v[178:181], v[40:43]
	v_mfma_f32_16x16x32_bf16 v[32:35], v[156:159], v[196:199], v[32:35]
	v_mfma_f32_16x16x32_bf16 v[24:27], v[170:173], v[196:199], v[24:27]
	v_mfma_f32_16x16x32_bf16 v[16:19], v[156:159], v[204:207], v[16:19]
	v_mfma_f32_16x16x32_bf16 v[8:11], v[170:173], v[204:207], v[8:11]
	v_mfma_f32_16x16x32_bf16 v[4:7], v[156:159], v[212:215], v[4:7]
	v_mfma_f32_16x16x32_bf16 v[0:3], v[170:173], v[212:215], v[0:3]
	v_mfma_f32_16x16x32_bf16 v[48:51], v[166:169], v[184:187], v[48:51]
	v_mfma_f32_16x16x32_bf16 v[40:43], v[174:177], v[184:187], v[40:43]
	v_mfma_f32_16x16x32_bf16 v[32:35], v[166:169], v[200:203], v[32:35]
	v_mfma_f32_16x16x32_bf16 v[24:27], v[174:177], v[200:203], v[24:27]
	v_mfma_f32_16x16x32_bf16 v[16:19], v[166:169], v[208:211], v[16:19]
	v_mfma_f32_16x16x32_bf16 v[8:11], v[174:177], v[208:211], v[8:11]
	v_mfma_f32_16x16x32_bf16 v[4:7], v[166:169], v[216:219], v[4:7]
	v_mfma_f32_16x16x32_bf16 v[0:3], v[174:177], v[216:219], v[0:3]
	s_barrier
	s_add_i32 s60, s60, 2
	s_add_u32 s50, s50, 0x100
	s_addc_u32 s51, s51, 0
	s_add_u32 s58, s58, 0x100
	s_addc_u32 s59, s59, 0
	s_cmp_gt_u32 s60, 29
	s_cbranch_scc0 .LBB0_180
	s_setprio 0
	s_and_b64 vcc, exec, s[36:37]
	s_cbranch_vccz .LBB0_183
	s_barrier

; #define PG8_STAGE(bufoff, gbase, voff) do { _Pragma("unroll") for (int _i = 0; _i < 2; ++_i) \
;         __builtin_amdgcn_global_load_lds((const unsigned*)((const char*)(gbase) + (voff)[_i]), (PG8_LAS unsigned*)(lds + (bufoff) + ldsw + _i * 8192), 16, 0, 0); } while (0)
; #define PG8_LDA(dst, b, h) do { _Pragma("unroll") for (int m = 0; m < 4; ++m) _Pragma("unroll") for (int k = 0; k < 2; ++k) dst[m][k] = *(const PG8_LAS bf16x8*)(lds + PG8_SA(b, h) + aoff + m * 2048 + k * 1024); } while (0)
; #define PG8_LDB(dst, b, h) do { _Pragma("unroll") for (int n = 0; n < 2; ++n) _Pragma("unroll") for (int k = 0; k < 2; ++k) dst[n][k] = *(const PG8_LAS bf16x8*)(lds + PG8_SB(b, h) + boff + n * 2048 + k * 1024); } while (0)
; #define PG8_WAIT_V(n) asm volatile("s_waitcnt vmcnt(" #n ")" ::: "memory")
; #define PG8_WAIT_L(n) asm volatile("s_waitcnt lgkmcnt(" #n ")" ::: "memory")
; #define PG8_BAR __builtin_amdgcn_s_barrier()
; template <class Epi, class Sched, bool ALIGN_EPI = false, bool SP2 = false>
; __device__ __forceinline__ void gemm_phase(PG8_LAS unsigned char* lds, const Gemm g, const Sched& S, const Epi& E, const int tid_in) {
;     ...
;         const bool has_next = S.next(ui + 1, nxt);
;         const char* nA = has_next ? (const char*)g.A + (size_t)nxt.pm * tstep : cA; const char* nB = has_next ? (const char*)g.Bt + (size_t)nxt.pn * tstep : cB;
;         for (int t = 0; t < nt; t += 2) {
;             const bool last = (t == nt - 2);
;             const char* a1 = cA + (size_t)(t + 1) * kstep;
;             const char* a2 = last ? nA : cA + (size_t)(t + 2) * kstep; const char* b2 = last ? nB : cB + (size_t)(t + 2) * kstep;
;             const char* a3 = a2 + kstep; const char* b3 = b2 + kstep;
;             if (last && has_next) S.a_ready(nxt);
;             if constexpr (SP2) {
;             PG8_LDB(B0, 0, 0); PG8_LDB(B1, 0, 1); PG8_SCHED; PG8_LDA(At, 0, 0); PG8_STAGE(PG8_SA(1, 1), a1 + hstep, voffA);
;             PG8_WAIT_V(8); PG8_WAIT_L(0); PG8_BAR; PG8_MMA(0, 0, At, B0); PG8_MMA(0, 1, At, B1); PG8_BAR; PG8_SCHED;
;     ...
; #pragma unroll
;         for (int a = 0; a < 2; ++a)
; #pragma unroll
;             for (int b = 0; b < 2; ++b)
; #pragma unroll
;                 for (int m = 0; m < 4; ++m)
; #pragma unroll
;                     for (int n = 0; n < 2; ++n) acc[a][b][m][n] = (f32x4){0.f, 0.f, 0.f, 0.f};
;         cur = nxt; cA = nA; cB = nB; ++ui;
.LBB0_592:
	s_ashr_i32 s57, s56, 31
	s_lshl_b64 s[12:13], s[56:57], 20
	v_readlane_b32 s36, v255, 4
	v_readlane_b32 s37, v255, 5
	s_add_u32 s36, s36, s12
	s_addc_u32 s37, s37, s13
	s_and_b64 s[12:13], s[38:39], exec
	s_cselect_b32 s12, s37, s11
	s_cselect_b32 s13, s36, s10
	s_ashr_i32 s55, s54, 31
	s_lshl_b64 s[42:43], s[54:55], 20
	s_add_u32 s58, s14, s42
	s_addc_u32 s59, s15, s43
	s_and_b64 s[42:43], s[38:39], exec
	s_cselect_b32 s41, s59, s9
	s_cselect_b32 s44, s58, s8
	s_add_u32 s42, s10, 0x80080
	s_addc_u32 s43, s11, 0
	s_add_u32 s45, s8, 0x100
	v_mov_b32_e32 v0, 0
	s_addc_u32 s55, s9, 0
	s_mov_b32 s57, -2
	v_mov_b32_e32 v1, v0
	v_mov_b32_e32 v2, v0
	v_mov_b32_e32 v3, v0
	v_mov_b32_e32 v4, v0
	v_mov_b32_e32 v5, v0
	v_mov_b32_e32 v6, v0
	v_mov_b32_e32 v7, v0
	v_mov_b32_e32 v16, v0
	v_mov_b32_e32 v17, v0
	v_mov_b32_e32 v18, v0
	v_mov_b32_e32 v19, v0
	v_mov_b32_e32 v20, v0
	v_mov_b32_e32 v21, v0
	v_mov_b32_e32 v22, v0
	v_mov_b32_e32 v23, v0
	v_mov_b32_e32 v32, v0
	v_mov_b32_e32 v33, v0
	v_mov_b32_e32 v34, v0
	v_mov_b32_e32 v35, v0
	v_mov_b32_e32 v36, v0
	v_mov_b32_e32 v37, v0
	v_mov_b32_e32 v38, v0
	v_mov_b32_e32 v39, v0
	v_mov_b32_e32 v48, v0
	v_mov_b32_e32 v49, v0
	v_mov_b32_e32 v50, v0
	v_mov_b32_e32 v51, v0
	v_mov_b32_e32 v52, v0
	v_mov_b32_e32 v53, v0
	v_mov_b32_e32 v54, v0
	v_mov_b32_e32 v55, v0
	v_mov_b32_e32 v8, v0
	v_mov_b32_e32 v9, v0
	v_mov_b32_e32 v10, v0
	v_mov_b32_e32 v11, v0
	v_mov_b32_e32 v12, v0
	v_mov_b32_e32 v13, v0
	v_mov_b32_e32 v14, v0
	v_mov_b32_e32 v15, v0
	v_mov_b32_e32 v24, v0
	v_mov_b32_e32 v25, v0
	v_mov_b32_e32 v26, v0
	v_mov_b32_e32 v27, v0
	v_mov_b32_e32 v28, v0
	v_mov_b32_e32 v29, v0
	v_mov_b32_e32 v30, v0
	v_mov_b32_e32 v31, v0
	v_mov_b32_e32 v40, v0
	v_mov_b32_e32 v41, v0
	v_mov_b32_e32 v42, v0
	v_mov_b32_e32 v43, v0
	v_mov_b32_e32 v44, v0
	v_mov_b32_e32 v45, v0
	v_mov_b32_e32 v46, v0
	v_mov_b32_e32 v47, v0
	v_mov_b32_e32 v56, v0
	v_mov_b32_e32 v57, v0
	v_mov_b32_e32 v58, v0
	v_mov_b32_e32 v59, v0
	v_mov_b32_e32 v60, v0
	v_mov_b32_e32 v61, v0
	v_mov_b32_e32 v62, v0
	v_mov_b32_e32 v63, v0
	v_mov_b32_e32 v72, v0
	v_mov_b32_e32 v73, v0
	v_mov_b32_e32 v74, v0
	v_mov_b32_e32 v75, v0
	v_mov_b32_e32 v76, v0
	v_mov_b32_e32 v77, v0
	v_mov_b32_e32 v78, v0
	v_mov_b32_e32 v79, v0
	v_mov_b32_e32 v98, v0
	v_mov_b32_e32 v99, v0
	v_mov_b32_e32 v100, v0
	v_mov_b32_e32 v101, v0
	v_mov_b32_e32 v102, v0
	v_mov_b32_e32 v103, v0
	v_mov_b32_e32 v104, v0
	v_mov_b32_e32 v105, v0
	v_mov_b32_e32 v122, v0
	v_mov_b32_e32 v123, v0
	v_mov_b32_e32 v124, v0
	v_mov_b32_e32 v125, v0
	v_mov_b32_e32 v126, v0
	v_mov_b32_e32 v127, v0
	v_mov_b32_e32 v128, v0
	v_mov_b32_e32 v129, v0
	v_mov_b32_e32 v146, v0
	v_mov_b32_e32 v147, v0
	v_mov_b32_e32 v148, v0
	v_mov_b32_e32 v149, v0
	v_mov_b32_e32 v150, v0
	v_mov_b32_e32 v151, v0
	v_mov_b32_e32 v152, v0
	v_mov_b32_e32 v153, v0
	v_mov_b32_e32 v80, v0
	v_mov_b32_e32 v81, v0
	v_mov_b32_e32 v82, v0
	v_mov_b32_e32 v83, v0
	v_mov_b32_e32 v84, v0
	v_mov_b32_e32 v85, v0
	v_mov_b32_e32 v86, v0
	v_mov_b32_e32 v87, v0
	v_mov_b32_e32 v114, v0
	v_mov_b32_e32 v115, v0
	v_mov_b32_e32 v116, v0
	v_mov_b32_e32 v117, v0
	v_mov_b32_e32 v118, v0
	v_mov_b32_e32 v119, v0
	v_mov_b32_e32 v120, v0
	v_mov_b32_e32 v121, v0
	v_mov_b32_e32 v138, v0
	v_mov_b32_e32 v139, v0
	v_mov_b32_e32 v140, v0
	v_mov_b32_e32 v141, v0
	v_mov_b32_e32 v142, v0
	v_mov_b32_e32 v143, v0
	v_mov_b32_e32 v144, v0
	v_mov_b32_e32 v145, v0
	v_mov_b32_e32 v154, v0
	v_mov_b32_e32 v155, v0
	v_mov_b32_e32 v156, v0
	v_mov_b32_e32 v157, v0
	v_mov_b32_e32 v158, v0
	v_mov_b32_e32 v159, v0
	v_mov_b32_e32 v160, v0
	v_mov_b32_e32 v161, v0
	v_readfirstlane_b32 s70, v241
	s_nop 3
	s_lshr_b32 s70, s70, 6
	s_cmp_ge_u32 s70, 4
	s_cbranch_scc0 .Lprio_done_593
	s_setprio 1
.Lprio_done_593:
.LBB0_593:
	s_add_u32 s8, s42, 0xfff80080
	s_addc_u32 s9, s43, -1
	s_add_i32 s61, 0, 0x10000
	s_cmp_eq_u32 s57, 28
	s_cselect_b32 s11, s12, s9
	s_cselect_b32 s10, s13, s8
	s_cselect_b32 s9, s41, s55
	s_cselect_b32 s8, s44, s45
	s_add_i32 s64, 0, 0x14000
	s_waitcnt vmcnt(0)
	v_add_u32_e32 v92, s61, v196
	v_add_u32_e32 v96, s64, v196
	ds_read_b128 v[64:67], v92
	ds_read_b128 v[68:71], v92 offset:1024
	ds_read_b128 v[88:91], v92 offset:2048
	ds_read_b128 v[92:95], v92 offset:3072
	ds_read_b128 v[106:109], v96
	ds_read_b128 v[110:113], v96 offset:1024
	ds_read_b128 v[130:133], v96 offset:2048
	ds_read_b128 v[134:137], v96 offset:3072
	v_lshl_add_u64 v[180:181], s[42:43], 0, v[172:173]
	s_add_i32 m0, s20, 0xc000
	ds_read_b128 v[176:179], v198
	ds_read_b128 v[200:203], v198 offset:1024
	ds_read_b128 v[204:207], v198 offset:2048
	ds_read_b128 v[208:211], v198 offset:3072
	ds_read_b128 v[212:215], v198 offset:4096
	ds_read_b128 v[216:219], v198 offset:5120
	ds_read_b128 v[220:223], v198 offset:6144
	ds_read_b128 v[242:245], v198 offset:7168
	global_load_lds_dwordx4 v[180:181], off
	v_lshl_add_u64 v[180:181], s[42:43], 0, v[174:175]
	s_add_i32 m0, s20, 0xe000
	s_nop 0
	global_load_lds_dwordx4 v[180:181], off
	s_waitcnt vmcnt(8)
	s_waitcnt lgkmcnt(0)
	s_barrier
; #define PG8_STAGE(bufoff, gbase, voff) do { _Pragma("unroll") for (int _i = 0; _i < 2; ++_i) \
;         __builtin_amdgcn_global_load_lds((const unsigned*)((const char*)(gbase) + (voff)[_i]), (PG8_LAS unsigned*)(lds + (bufoff) + ldsw + _i * 8192), 16, 0, 0); } while (0)
; #define PG8_LDA(dst, b, h) do { _Pragma("unroll") for (int m = 0; m < 4; ++m) _Pragma("unroll") for (int k = 0; k < 2; ++k) dst[m][k] = *(const PG8_LAS bf16x8*)(lds + PG8_SA(b, h) + aoff + m * 2048 + k * 1024); } while (0)
; #define PG8_LDB(dst, b, h) do { _Pragma("unroll") for (int n = 0; n < 2; ++n) _Pragma("unroll") for (int k = 0; k < 2; ++k) dst[n][k] = *(const PG8_LAS bf16x8*)(lds + PG8_SB(b, h) + boff + n * 2048 + k * 1024); } while (0)
; #define PG8_MMA(ai, bj, At, Bt) do { __builtin_amdgcn_s_setprio(1); _Pragma("unroll") for (int m = 0; m < 4; ++m) _Pragma("unroll") for (int n = 0; n < 2; ++n) _Pragma("unroll") for (int k = 0; k < 2; ++k) \
;         acc[ai][bj][m][n] = __builtin_amdgcn_mfma_f32_16x16x32_bf16(Bt[n][k], At[m][k], acc[ai][bj][m][n], 0, 0, 0); __builtin_amdgcn_s_setprio(0); } while (0)
; #define PG8_WAIT_V(n) asm volatile("s_waitcnt vmcnt(" #n ")" ::: "memory")
; #define PG8_WAIT_L(n) asm volatile("s_waitcnt lgkmcnt(" #n ")" ::: "memory")
; #define PG8_BAR __builtin_amdgcn_s_barrier()
; #define PG8_SCHED __builtin_amdgcn_sched_barrier(0)
; template <class Epi, class Sched, bool ALIGN_EPI = false, bool SP2 = false>
; __device__ __forceinline__ void gemm_phase(PG8_LAS unsigned char* lds, const Gemm g, const Sched& S, const Epi& E, const int tid_in) {
;     ...
;             PG8_LDB(B0, 0, 0); PG8_LDB(B1, 0, 1); PG8_SCHED; PG8_LDA(At, 0, 0); PG8_STAGE(PG8_SA(1, 1), a1 + hstep, voffA);
;             PG8_WAIT_V(8); PG8_WAIT_L(0); PG8_BAR; PG8_MMA(0, 0, At, B0); PG8_MMA(0, 1, At, B1); PG8_BAR; PG8_SCHED;
;             PG8_LDA(At, 0, 1); PG8_STAGE(PG8_SB(0, 0), b2, voffB); PG8_STAGE(PG8_SB(0, 1), b2 + hstep, voffB); PG8_STAGE(PG8_SA(0, 0), a2, voffA);
;             PG8_WAIT_V(8); PG8_WAIT_L(0); PG8_BAR; PG8_MMA(1, 0, At, B0); PG8_MMA(1, 1, At, B1); PG8_BAR; PG8_SCHED;
	s_waitcnt lgkmcnt(0)
	v_mfma_f32_16x16x32_bf16 v[158:161], v[64:67], v[176:179], v[158:161]
	v_mfma_f32_16x16x32_bf16 v[154:157], v[88:91], v[176:179], v[154:157]
	v_mfma_f32_16x16x32_bf16 v[142:145], v[64:67], v[204:207], v[142:145]
	v_mfma_f32_16x16x32_bf16 v[138:141], v[88:91], v[204:207], v[138:141]
	v_mfma_f32_16x16x32_bf16 v[118:121], v[64:67], v[212:215], v[118:121]
	v_mfma_f32_16x16x32_bf16 v[114:117], v[88:91], v[212:215], v[114:117]
	v_mfma_f32_16x16x32_bf16 v[84:87], v[64:67], v[220:223], v[84:87]
	v_mfma_f32_16x16x32_bf16 v[80:83], v[88:91], v[220:223], v[80:83]
	v_mfma_f32_16x16x32_bf16 v[158:161], v[68:71], v[200:203], v[158:161]
	v_mfma_f32_16x16x32_bf16 v[154:157], v[92:95], v[200:203], v[154:157]
	v_mfma_f32_16x16x32_bf16 v[142:145], v[68:71], v[208:211], v[142:145]
	v_mfma_f32_16x16x32_bf16 v[138:141], v[92:95], v[208:211], v[138:141]
	v_mfma_f32_16x16x32_bf16 v[118:121], v[68:71], v[216:219], v[118:121]
	v_mfma_f32_16x16x32_bf16 v[114:117], v[92:95], v[216:219], v[114:117]
	v_mfma_f32_16x16x32_bf16 v[84:87], v[68:71], v[242:245], v[84:87]
	v_mfma_f32_16x16x32_bf16 v[80:83], v[92:95], v[242:245], v[80:83]
	v_mfma_f32_16x16x32_bf16 v[150:153], v[106:109], v[176:179], v[150:153]
	v_mfma_f32_16x16x32_bf16 v[146:149], v[130:133], v[176:179], v[146:149]
	v_mfma_f32_16x16x32_bf16 v[126:129], v[106:109], v[204:207], v[126:129]
	v_mfma_f32_16x16x32_bf16 v[122:125], v[130:133], v[204:207], v[122:125]
	v_mfma_f32_16x16x32_bf16 v[102:105], v[106:109], v[212:215], v[102:105]
	v_mfma_f32_16x16x32_bf16 v[98:101], v[130:133], v[212:215], v[98:101]
	v_mfma_f32_16x16x32_bf16 v[76:79], v[106:109], v[220:223], v[76:79]
	v_mfma_f32_16x16x32_bf16 v[72:75], v[130:133], v[220:223], v[72:75]
	v_mfma_f32_16x16x32_bf16 v[150:153], v[110:113], v[200:203], v[150:153]
	v_mfma_f32_16x16x32_bf16 v[146:149], v[134:137], v[200:203], v[146:149]
	v_mfma_f32_16x16x32_bf16 v[126:129], v[110:113], v[208:211], v[126:129]
	v_mfma_f32_16x16x32_bf16 v[122:125], v[134:137], v[208:211], v[122:125]
	v_mfma_f32_16x16x32_bf16 v[102:105], v[110:113], v[216:219], v[102:105]
	v_mfma_f32_16x16x32_bf16 v[98:101], v[134:137], v[216:219], v[98:101]
	v_mfma_f32_16x16x32_bf16 v[76:79], v[110:113], v[242:245], v[76:79]
	v_mfma_f32_16x16x32_bf16 v[72:75], v[134:137], v[242:245], v[72:75]
	s_barrier
	s_add_i32 s61, s61, s19
	v_lshl_add_u64 v[180:181], s[8:9], 0, v[164:165]
	s_mov_b32 m0, s61
	ds_read_b128 v[176:179], v198 offset:16384
	ds_read_b128 v[200:203], v198 offset:17408
	ds_read_b128 v[204:207], v198 offset:18432
	ds_read_b128 v[208:211], v198 offset:19456
	ds_read_b128 v[212:215], v198 offset:20480
	ds_read_b128 v[216:219], v198 offset:21504
	ds_read_b128 v[220:223], v198 offset:22528
	ds_read_b128 v[242:245], v198 offset:23552
	global_load_lds_dwordx4 v[180:181], off
	s_add_i32 m0, s61, 0x2000
	s_add_u32 s62, s8, 0x80000
	v_lshl_add_u64 v[184:185], s[8:9], 0, v[168:169]
	s_addc_u32 s63, s9, 0
	s_add_i32 s61, s64, s19
	global_load_lds_dwordx4 v[184:185], off
	v_lshl_add_u64 v[186:187], s[62:63], 0, v[164:165]
	s_mov_b32 m0, s61
	v_lshl_add_u64 v[224:225], s[10:11], 0, v[166:167]
	global_load_lds_dwordx4 v[186:187], off
	v_lshl_add_u64 v[186:187], s[62:63], 0, v[168:169]
	s_add_i32 m0, s61, 0x2000
	s_nop 0
	global_load_lds_dwordx4 v[186:187], off
	v_lshl_add_u64 v[186:187], s[10:11], 0, v[162:163]
	s_mov_b32 m0, s20
	s_nop 0
	global_load_lds_dwordx4 v[186:187], off
	s_mov_b32 m0, s22
	s_nop 0
	global_load_lds_dwordx4 v[224:225], off
	s_waitcnt vmcnt(8)
	s_waitcnt lgkmcnt(0)
	s_barrier
	s_waitcnt lgkmcnt(0)
	v_mfma_f32_16x16x32_bf16 v[60:63], v[64:67], v[176:179], v[60:63]
	v_mfma_f32_16x16x32_bf16 v[56:59], v[88:91], v[176:179], v[56:59]
	v_mfma_f32_16x16x32_bf16 v[44:47], v[64:67], v[204:207], v[44:47]
	v_mfma_f32_16x16x32_bf16 v[40:43], v[88:91], v[204:207], v[40:43]
	v_mfma_f32_16x16x32_bf16 v[28:31], v[64:67], v[212:215], v[28:31]
	v_mfma_f32_16x16x32_bf16 v[24:27], v[88:91], v[212:215], v[24:27]
	v_mfma_f32_16x16x32_bf16 v[12:15], v[64:67], v[220:223], v[12:15]
	v_mfma_f32_16x16x32_bf16 v[8:11], v[88:91], v[220:223], v[8:11]
	v_mfma_f32_16x16x32_bf16 v[60:63], v[68:71], v[200:203], v[60:63]
	v_mfma_f32_16x16x32_bf16 v[56:59], v[92:95], v[200:203], v[56:59]
	v_mfma_f32_16x16x32_bf16 v[44:47], v[68:71], v[208:211], v[44:47]
	v_mfma_f32_16x16x32_bf16 v[40:43], v[92:95], v[208:211], v[40:43]
	v_mfma_f32_16x16x32_bf16 v[28:31], v[68:71], v[216:219], v[28:31]
	v_mfma_f32_16x16x32_bf16 v[24:27], v[92:95], v[216:219], v[24:27]
	v_mfma_f32_16x16x32_bf16 v[12:15], v[68:71], v[242:245], v[12:15]
	v_mfma_f32_16x16x32_bf16 v[8:11], v[92:95], v[242:245], v[8:11]
	v_mfma_f32_16x16x32_bf16 v[52:55], v[106:109], v[176:179], v[52:55]
	v_mfma_f32_16x16x32_bf16 v[48:51], v[130:133], v[176:179], v[48:51]
	v_mfma_f32_16x16x32_bf16 v[36:39], v[106:109], v[204:207], v[36:39]
	v_mfma_f32_16x16x32_bf16 v[32:35], v[130:133], v[204:207], v[32:35]
	v_mfma_f32_16x16x32_bf16 v[20:23], v[106:109], v[212:215], v[20:23]
	v_mfma_f32_16x16x32_bf16 v[16:19], v[130:133], v[212:215], v[16:19]
	v_mfma_f32_16x16x32_bf16 v[4:7], v[106:109], v[220:223], v[4:7]
	v_mfma_f32_16x16x32_bf16 v[0:3], v[130:133], v[220:223], v[0:3]
	v_mfma_f32_16x16x32_bf16 v[52:55], v[110:113], v[200:203], v[52:55]
	v_mfma_f32_16x16x32_bf16 v[48:51], v[134:137], v[200:203], v[48:51]
	v_mfma_f32_16x16x32_bf16 v[36:39], v[110:113], v[208:211], v[36:39]
	v_mfma_f32_16x16x32_bf16 v[32:35], v[134:137], v[208:211], v[32:35]
	v_mfma_f32_16x16x32_bf16 v[20:23], v[110:113], v[216:219], v[20:23]
	v_mfma_f32_16x16x32_bf16 v[16:19], v[134:137], v[216:219], v[16:19]
	v_mfma_f32_16x16x32_bf16 v[4:7], v[110:113], v[242:245], v[4:7]
	v_mfma_f32_16x16x32_bf16 v[0:3], v[134:137], v[242:245], v[0:3]
	s_barrier
; #define PG8_STAGE(bufoff, gbase, voff) do { _Pragma("unroll") for (int _i = 0; _i < 2; ++_i) \
;         __builtin_amdgcn_global_load_lds((const unsigned*)((const char*)(gbase) + (voff)[_i]), (PG8_LAS unsigned*)(lds + (bufoff) + ldsw + _i * 8192), 16, 0, 0); } while (0)
; #define PG8_LDA(dst, b, h) do { _Pragma("unroll") for (int m = 0; m < 4; ++m) _Pragma("unroll") for (int k = 0; k < 2; ++k) dst[m][k] = *(const PG8_LAS bf16x8*)(lds + PG8_SA(b, h) + aoff + m * 2048 + k * 1024); } while (0)
; #define PG8_LDB(dst, b, h) do { _Pragma("unroll") for (int n = 0; n < 2; ++n) _Pragma("unroll") for (int k = 0; k < 2; ++k) dst[n][k] = *(const PG8_LAS bf16x8*)(lds + PG8_SB(b, h) + boff + n * 2048 + k * 1024); } while (0)
; #define PG8_MMA(ai, bj, At, Bt) do { __builtin_amdgcn_s_setprio(1); _Pragma("unroll") for (int m = 0; m < 4; ++m) _Pragma("unroll") for (int n = 0; n < 2; ++n) _Pragma("unroll") for (int k = 0; k < 2; ++k) \
;         acc[ai][bj][m][n] = __builtin_amdgcn_mfma_f32_16x16x32_bf16(Bt[n][k], At[m][k], acc[ai][bj][m][n], 0, 0, 0); __builtin_amdgcn_s_setprio(0); } while (0)
; #define PG8_WAIT_V(n) asm volatile("s_waitcnt vmcnt(" #n ")" ::: "memory")
; #define PG8_WAIT_L(n) asm volatile("s_waitcnt lgkmcnt(" #n ")" ::: "memory")
; #define PG8_BAR __builtin_amdgcn_s_barrier()
; #define PG8_SCHED __builtin_amdgcn_sched_barrier(0)
; template <class Epi, class Sched, bool ALIGN_EPI = false, bool SP2 = false>
; __device__ __forceinline__ void gemm_phase(PG8_LAS unsigned char* lds, const Gemm g, const Sched& S, const Epi& E, const int tid_in) {
;     ...
;             PG8_LDB(B0, 1, 0); PG8_LDB(B1, 1, 1); PG8_SCHED; PG8_LDA(At, 1, 0); PG8_STAGE(PG8_SA(0, 1), a2 + hstep, voffA);
;             PG8_WAIT_V(8); PG8_WAIT_L(0); PG8_BAR; PG8_MMA(0, 0, At, B0); PG8_MMA(0, 1, At, B1); PG8_BAR; PG8_SCHED;
	s_add_i32 s61, 0, 0x18000
	s_add_i32 s62, 0, 0x1c000
	v_add_u32_e32 v92, s61, v196
	v_add_u32_e32 v96, s62, v196
	ds_read_b128 v[64:67], v92
	ds_read_b128 v[68:71], v92 offset:1024
	ds_read_b128 v[88:91], v92 offset:2048
	ds_read_b128 v[92:95], v92 offset:3072
	ds_read_b128 v[106:109], v96
	ds_read_b128 v[110:113], v96 offset:1024
	ds_read_b128 v[130:133], v96 offset:2048
	ds_read_b128 v[134:137], v96 offset:3072
	s_add_u32 s10, s10, 0x80000
	s_addc_u32 s11, s11, 0
	s_mov_b32 m0, s23
	v_lshl_add_u64 v[250:251], s[10:11], 0, v[162:163]
	ds_read_b128 v[176:179], v198 offset:32768
	ds_read_b128 v[200:203], v198 offset:33792
	ds_read_b128 v[204:207], v198 offset:34816
	ds_read_b128 v[208:211], v198 offset:35840
	ds_read_b128 v[212:215], v198 offset:36864
	ds_read_b128 v[216:219], v198 offset:37888
	ds_read_b128 v[220:223], v198 offset:38912
	ds_read_b128 v[242:245], v198 offset:39936
	global_load_lds_dwordx4 v[250:251], off
	v_lshl_add_u64 v[250:251], s[10:11], 0, v[166:167]
	s_mov_b32 m0, s34
	s_nop 0
	global_load_lds_dwordx4 v[250:251], off
	s_waitcnt vmcnt(8)
	s_waitcnt lgkmcnt(0)
	s_barrier
	s_waitcnt lgkmcnt(0)
	v_mfma_f32_16x16x32_bf16 v[158:161], v[64:67], v[176:179], v[158:161]
	v_mfma_f32_16x16x32_bf16 v[154:157], v[88:91], v[176:179], v[154:157]
	v_mfma_f32_16x16x32_bf16 v[142:145], v[64:67], v[204:207], v[142:145]
	v_mfma_f32_16x16x32_bf16 v[138:141], v[88:91], v[204:207], v[138:141]
	v_mfma_f32_16x16x32_bf16 v[118:121], v[64:67], v[212:215], v[118:121]
	v_mfma_f32_16x16x32_bf16 v[114:117], v[88:91], v[212:215], v[114:117]
	v_mfma_f32_16x16x32_bf16 v[84:87], v[64:67], v[220:223], v[84:87]
	v_mfma_f32_16x16x32_bf16 v[80:83], v[88:91], v[220:223], v[80:83]
	v_mfma_f32_16x16x32_bf16 v[158:161], v[68:71], v[200:203], v[158:161]
	v_mfma_f32_16x16x32_bf16 v[154:157], v[92:95], v[200:203], v[154:157]
	v_mfma_f32_16x16x32_bf16 v[142:145], v[68:71], v[208:211], v[142:145]
	v_mfma_f32_16x16x32_bf16 v[138:141], v[92:95], v[208:211], v[138:141]
	v_mfma_f32_16x16x32_bf16 v[118:121], v[68:71], v[216:219], v[118:121]
	v_mfma_f32_16x16x32_bf16 v[114:117], v[92:95], v[216:219], v[114:117]
	v_mfma_f32_16x16x32_bf16 v[84:87], v[68:71], v[242:245], v[84:87]
	v_mfma_f32_16x16x32_bf16 v[80:83], v[92:95], v[242:245], v[80:83]
	v_mfma_f32_16x16x32_bf16 v[150:153], v[106:109], v[176:179], v[150:153]
	v_mfma_f32_16x16x32_bf16 v[146:149], v[130:133], v[176:179], v[146:149]
	v_mfma_f32_16x16x32_bf16 v[126:129], v[106:109], v[204:207], v[126:129]
	v_mfma_f32_16x16x32_bf16 v[122:125], v[130:133], v[204:207], v[122:125]
	v_mfma_f32_16x16x32_bf16 v[102:105], v[106:109], v[212:215], v[102:105]
	v_mfma_f32_16x16x32_bf16 v[98:101], v[130:133], v[212:215], v[98:101]
	v_mfma_f32_16x16x32_bf16 v[76:79], v[106:109], v[220:223], v[76:79]
	v_mfma_f32_16x16x32_bf16 v[72:75], v[130:133], v[220:223], v[72:75]
	v_mfma_f32_16x16x32_bf16 v[150:153], v[110:113], v[200:203], v[150:153]
	v_mfma_f32_16x16x32_bf16 v[146:149], v[134:137], v[200:203], v[146:149]
	v_mfma_f32_16x16x32_bf16 v[126:129], v[110:113], v[208:211], v[126:129]
	v_mfma_f32_16x16x32_bf16 v[122:125], v[134:137], v[208:211], v[122:125]
	v_mfma_f32_16x16x32_bf16 v[102:105], v[110:113], v[216:219], v[102:105]
	v_mfma_f32_16x16x32_bf16 v[98:101], v[134:137], v[216:219], v[98:101]
	v_mfma_f32_16x16x32_bf16 v[76:79], v[110:113], v[242:245], v[76:79]
	v_mfma_f32_16x16x32_bf16 v[72:75], v[134:137], v[242:245], v[72:75]
	s_barrier
; #define PG8_STAGE(bufoff, gbase, voff) do { _Pragma("unroll") for (int _i = 0; _i < 2; ++_i) \
;         __builtin_amdgcn_global_load_lds((const unsigned*)((const char*)(gbase) + (voff)[_i]), (PG8_LAS unsigned*)(lds + (bufoff) + ldsw + _i * 8192), 16, 0, 0); } while (0)
; #define PG8_LDA(dst, b, h) do { _Pragma("unroll") for (int m = 0; m < 4; ++m) _Pragma("unroll") for (int k = 0; k < 2; ++k) dst[m][k] = *(const PG8_LAS bf16x8*)(lds + PG8_SA(b, h) + aoff + m * 2048 + k * 1024); } while (0)
; #define PG8_WAIT_V(n) asm volatile("s_waitcnt vmcnt(" #n ")" ::: "memory")
; #define PG8_WAIT_L(n) asm volatile("s_waitcnt lgkmcnt(" #n ")" ::: "memory")
; #define PG8_BAR __builtin_amdgcn_s_barrier()
; template <class Epi, class Sched, bool ALIGN_EPI = false, bool SP2 = false>
; __device__ __forceinline__ void gemm_phase(PG8_LAS unsigned char* lds, const Gemm g, const Sched& S, const Epi& E, const int tid_in) {
;     ...
;         for (int t = 0; t < nt; t += 2) {
;             const bool last = (t == nt - 2);
;             const char* a1 = cA + (size_t)(t + 1) * kstep;
;             const char* a2 = last ? nA : cA + (size_t)(t + 2) * kstep; const char* b2 = last ? nB : cB + (size_t)(t + 2) * kstep;
;             const char* a3 = a2 + kstep; const char* b3 = b2 + kstep;
;             if (last && has_next) S.a_ready(nxt);
;             if constexpr (SP2) {
;             PG8_LDB(B0, 0, 0); PG8_LDB(B1, 0, 1); PG8_SCHED; PG8_LDA(At, 0, 0); PG8_STAGE(PG8_SA(1, 1), a1 + hstep, voffA);
;             PG8_WAIT_V(8); PG8_WAIT_L(0); PG8_BAR; PG8_MMA(0, 0, At, B0); PG8_MMA(0, 1, At, B1); PG8_BAR; PG8_SCHED;
;             PG8_LDA(At, 0, 1); PG8_STAGE(PG8_SB(0, 0), b2, voffB); PG8_STAGE(PG8_SB(0, 1), b2 + hstep, voffB); PG8_STAGE(PG8_SA(0, 0), a2, voffA);
;             PG8_WAIT_V(8); PG8_WAIT_L(0); PG8_BAR; PG8_MMA(1, 0, At, B0); PG8_MMA(1, 1, At, B1); PG8_BAR; PG8_SCHED;
;             PG8_LDB(B0, 1, 0); PG8_LDB(B1, 1, 1); PG8_SCHED; PG8_LDA(At, 1, 0); PG8_STAGE(PG8_SA(0, 1), a2 + hstep, voffA);
;             PG8_WAIT_V(8); PG8_WAIT_L(0); PG8_BAR; PG8_MMA(0, 0, At, B0); PG8_MMA(0, 1, At, B1); PG8_BAR; PG8_SCHED;
;             PG8_LDA(At, 1, 1); PG8_STAGE(PG8_SB(1, 0), b3, voffB); PG8_STAGE(PG8_SB(1, 1), b3 + hstep, voffB); PG8_STAGE(PG8_SA(1, 0), a3, voffA);
;             PG8_WAIT_V(8); PG8_WAIT_L(0); PG8_BAR; PG8_MMA(1, 0, At, B0); PG8_MMA(1, 1, At, B1); PG8_BAR; PG8_SCHED;
	s_add_i32 s10, s61, s19
	v_lshl_add_u64 v[180:181], v[180:181], 0, s[2:3]
	s_mov_b32 m0, s10
	ds_read_b128 v[176:179], v198 offset:49152
	ds_read_b128 v[200:203], v198 offset:50176
	ds_read_b128 v[204:207], v198 offset:51200
	ds_read_b128 v[208:211], v198 offset:52224
	ds_read_b128 v[212:215], v198 offset:53248
	ds_read_b128 v[216:219], v198 offset:54272
	ds_read_b128 v[220:223], v198 offset:55296
	ds_read_b128 v[242:245], v198 offset:56320
	global_load_lds_dwordx4 v[180:181], off
	s_add_i32 m0, s10, 0x2000
	s_add_u32 s8, s8, 0x80080
	v_lshl_add_u64 v[180:181], v[184:185], 0, s[2:3]
	s_addc_u32 s9, s9, 0
	s_add_i32 s10, s62, s19
	global_load_lds_dwordx4 v[180:181], off
	v_lshl_add_u64 v[180:181], s[8:9], 0, v[164:165]
	s_mov_b32 m0, s10
	s_nop 0
	global_load_lds_dwordx4 v[180:181], off
	v_lshl_add_u64 v[180:181], s[8:9], 0, v[168:169]
	s_add_i32 m0, s10, 0x2000
	s_nop 0
	global_load_lds_dwordx4 v[180:181], off
	v_lshl_add_u64 v[180:181], v[186:187], 0, s[2:3]
	s_mov_b32 m0, s46
	s_nop 0
	global_load_lds_dwordx4 v[180:181], off
	v_lshl_add_u64 v[180:181], v[224:225], 0, s[2:3]
	s_mov_b32 m0, s49
	s_nop 0
	global_load_lds_dwordx4 v[180:181], off
	s_waitcnt vmcnt(8)
	s_waitcnt lgkmcnt(0)
	s_barrier
	s_waitcnt lgkmcnt(0)
	v_mfma_f32_16x16x32_bf16 v[60:63], v[64:67], v[176:179], v[60:63]
	v_mfma_f32_16x16x32_bf16 v[56:59], v[88:91], v[176:179], v[56:59]
	v_mfma_f32_16x16x32_bf16 v[44:47], v[64:67], v[204:207], v[44:47]
	v_mfma_f32_16x16x32_bf16 v[40:43], v[88:91], v[204:207], v[40:43]
	v_mfma_f32_16x16x32_bf16 v[28:31], v[64:67], v[212:215], v[28:31]
	v_mfma_f32_16x16x32_bf16 v[24:27], v[88:91], v[212:215], v[24:27]
	v_mfma_f32_16x16x32_bf16 v[12:15], v[64:67], v[220:223], v[12:15]
	v_mfma_f32_16x16x32_bf16 v[8:11], v[88:91], v[220:223], v[8:11]
	v_mfma_f32_16x16x32_bf16 v[60:63], v[68:71], v[200:203], v[60:63]
	v_mfma_f32_16x16x32_bf16 v[56:59], v[92:95], v[200:203], v[56:59]
	v_mfma_f32_16x16x32_bf16 v[44:47], v[68:71], v[208:211], v[44:47]
	v_mfma_f32_16x16x32_bf16 v[40:43], v[92:95], v[208:211], v[40:43]
	v_mfma_f32_16x16x32_bf16 v[28:31], v[68:71], v[216:219], v[28:31]
	v_mfma_f32_16x16x32_bf16 v[24:27], v[92:95], v[216:219], v[24:27]
	v_mfma_f32_16x16x32_bf16 v[12:15], v[68:71], v[242:245], v[12:15]
	v_mfma_f32_16x16x32_bf16 v[8:11], v[92:95], v[242:245], v[8:11]
	v_mfma_f32_16x16x32_bf16 v[52:55], v[106:109], v[176:179], v[52:55]
	v_mfma_f32_16x16x32_bf16 v[48:51], v[130:133], v[176:179], v[48:51]
	v_mfma_f32_16x16x32_bf16 v[36:39], v[106:109], v[204:207], v[36:39]
	v_mfma_f32_16x16x32_bf16 v[32:35], v[130:133], v[204:207], v[32:35]
	v_mfma_f32_16x16x32_bf16 v[20:23], v[106:109], v[212:215], v[20:23]
	v_mfma_f32_16x16x32_bf16 v[16:19], v[130:133], v[212:215], v[16:19]
	v_mfma_f32_16x16x32_bf16 v[4:7], v[106:109], v[220:223], v[4:7]
	v_mfma_f32_16x16x32_bf16 v[0:3], v[130:133], v[220:223], v[0:3]
	v_mfma_f32_16x16x32_bf16 v[52:55], v[110:113], v[200:203], v[52:55]
	v_mfma_f32_16x16x32_bf16 v[48:51], v[134:137], v[200:203], v[48:51]
	v_mfma_f32_16x16x32_bf16 v[36:39], v[110:113], v[208:211], v[36:39]
	v_mfma_f32_16x16x32_bf16 v[32:35], v[134:137], v[208:211], v[32:35]
	v_mfma_f32_16x16x32_bf16 v[20:23], v[110:113], v[216:219], v[20:23]
	v_mfma_f32_16x16x32_bf16 v[16:19], v[134:137], v[216:219], v[16:19]
	v_mfma_f32_16x16x32_bf16 v[4:7], v[110:113], v[242:245], v[4:7]
	v_mfma_f32_16x16x32_bf16 v[0:3], v[134:137], v[242:245], v[0:3]
	s_barrier
	s_add_i32 s57, s57, 2
	s_add_u32 s42, s42, 0x100
	s_addc_u32 s43, s43, 0
	s_add_u32 s45, s45, 0x100
	s_addc_u32 s55, s55, 0
	s_cmp_gt_u32 s57, 29
	s_cbranch_scc0 .LBB0_593
	s_setprio 0
	s_and_b64 vcc, exec, s[50:51]
	s_cbranch_vccz .LBB0_596
	s_barrier
